# nt (non-temporal) cache policy on once-read inputs x,p (P0), x (w_o epilogue) and on final out stores; on top of v6
# speedup vs baseline: 1.0369x; 1.0369x over previous
; __device__ __forceinline__ unsigned pk2(float a, float b) { f32x2_t v = {a, b}; bf16x2v_t r = __builtin_convertvector(v, bf16x2v_t); return __builtin_bit_cast(unsigned, r); }
; __device__ __forceinline__ void phase0(const Args& a, LAS unsigned char* lds, int gw_, int NGW, int wave, int lane_) {
;     ...
;     { bf16_t* PB = (bf16_t*)(ws + WS_PB);
;       for (int c = gt; c < T * PLE / 8; c += NGT) { const f32x4 v0 = *(const f32x4*)(a.p + (size_t)c * 8), v1 = *(const f32x4*)(a.p + (size_t)c * 8 + 4);
;           u32x4 o; o.x = pk2(v0[0], v0[1]); o.y = pk2(v0[2], v0[3]); o.z = pk2(v1[0], v1[1]); o.w = pk2(v1[2], v1[3]); *(u32x4*)(PB + (size_t)c * 8) = o; } }
.LBB0_90:
	global_load_dwordx4 v[6:9], v[0:1], off offset:-16 nt
	global_load_dwordx4 v[10:13], v[0:1], off nt
	v_add_u32_e32 v4, s4, v4
	v_cmp_lt_i32_e32 vcc, s2, v4
	v_lshl_add_u64 v[0:1], v[0:1], 0, s[10:11]
	s_or_b64 s[14:15], vcc, s[14:15]
	s_waitcnt vmcnt(1)
	v_cvt_pk_bf16_f32 v6, v6, v7
	v_cvt_pk_bf16_f32 v7, v8, v9
	s_waitcnt vmcnt(0)
	v_cvt_pk_bf16_f32 v8, v10, v11
	v_cvt_pk_bf16_f32 v9, v12, v13
	global_store_dwordx4 v[2:3], v[6:9], off
	v_lshl_add_u64 v[2:3], v[2:3], 0, s[12:13]
	s_andn2_b64 exec, exec, s[14:15]
	s_cbranch_execnz .LBB0_90

; __device__ __forceinline__ unsigned pk2(float a, float b) { f32x2_t v = {a, b}; bf16x2v_t r = __builtin_convertvector(v, bf16x2v_t); return __builtin_bit_cast(unsigned, r); }
; __device__ __forceinline__ void phase0(const Args& a, LAS unsigned char* lds, int gw_, int NGW, int wave, int lane_) {
;     ...
;     { bf16_t* XN = (bf16_t*)(ws + WS_XN);
;       f32x4 g[4];
; #pragma unroll
;       for (int j = 0; j < 4; ++j) g[j] = *(const f32x4*)(a.g_in + 4 * lane + 256 * j);
;       for (int m = gw; m < T; m += NGW) { const float* xr = a.x + (size_t)m * DM + 4 * lane; f32x4 v[4]; float s = 0.f;
; #pragma unroll
;           for (int j = 0; j < 4; ++j) { v[j] = *(const f32x4*)(xr + 256 * j); s += (v[j][0] * v[j][0] + v[j][1] * v[j][1]) + (v[j][2] * v[j][2] + v[j][3] * v[j][3]); }
;           const float rstd = rsqrtf(wave_sum(s) * (1.f / DM) + EPS);
; #pragma unroll
;           for (int j = 0; j < 4; ++j) { const f32x4 o = v[j] * rstd * g[j]; u32x2 w; w.x = pk2(o[0], o[1]); w.y = pk2(o[2], o[3]); *(u32x2*)(XN + (size_t)m * DM + 4 * lane + 256 * j) = w; } } }
.LBB0_93:
	global_load_dwordx4 v[28:31], v[18:19], off offset:-3072 nt
	global_load_dwordx4 v[32:35], v[18:19], off offset:-2048 nt
	global_load_dwordx4 v[36:39], v[18:19], off offset:-1024 nt
	global_load_dwordx4 v[40:43], v[18:19], off nt
	s_add_i32 s3, s3, s86
	v_lshl_add_u64 v[18:19], v[18:19], 0, s[4:5]
	s_cmpk_lt_i32 s3, 0x4000
	s_waitcnt vmcnt(3)
	v_pk_mul_f32 v[44:45], v[30:31], v[30:31]
	v_pk_mul_f32 v[46:47], v[28:29], v[28:29]
	s_waitcnt vmcnt(2)
	v_pk_mul_f32 v[48:49], v[34:35], v[34:35]
	v_pk_mul_f32 v[50:51], v[32:33], v[32:33]
	v_pk_mov_b32 v[56:57], v[46:47], v[44:45] op_sel:[1,0]
	v_mov_b32_e32 v47, v45
	v_pk_mov_b32 v[44:45], v[50:51], v[48:49] op_sel:[1,0]
	v_mov_b32_e32 v51, v49
	s_waitcnt vmcnt(0)
	v_mul_f32_e32 v55, v41, v41
	v_mul_f32_e32 v52, v37, v37
	v_mul_f32_e32 v54, v39, v39
	v_pk_add_f32 v[46:47], v[56:57], v[46:47]
	v_pk_add_f32 v[44:45], v[44:45], v[50:51]
	v_mul_f32_e32 v27, v40, v40
	v_mul_f32_e32 v58, v42, v42
	v_mul_f32_e32 v59, v43, v43
	v_pk_fma_f32 v[48:49], v[36:37], v[36:37], v[52:53] op_sel_hi:[1,1,0]
	v_pk_fma_f32 v[52:53], v[38:39], v[38:39], v[54:55] op_sel_hi:[1,1,0]
	v_pk_add_f32 v[46:47], v[46:47], v[46:47] op_sel:[0,1] op_sel_hi:[1,0]
	v_pk_add_f32 v[44:45], v[44:45], v[44:45] op_sel:[0,1] op_sel_hi:[1,0]
	v_mov_b32_e32 v49, v58
	v_mov_b32_e32 v53, v59
	v_mov_b32_e32 v47, v27
	v_mov_b32_e32 v45, v55
	v_pk_add_f32 v[48:49], v[48:49], v[52:53]
	v_pk_add_f32 v[44:45], v[46:47], v[44:45]
	s_nop 0
	v_pk_add_f32 v[44:45], v[44:45], v[48:49]
	s_nop 0
	v_add_f32_e32 v27, v44, v45
	ds_bpermute_b32 v44, v20, v27
	s_waitcnt lgkmcnt(0)
	v_add_f32_e32 v27, v27, v44
	ds_bpermute_b32 v44, v21, v27
	s_waitcnt lgkmcnt(0)
	v_add_f32_e32 v27, v27, v44
	ds_bpermute_b32 v44, v22, v27
	s_waitcnt lgkmcnt(0)
	v_add_f32_e32 v27, v27, v44
	ds_bpermute_b32 v44, v23, v27
	s_waitcnt lgkmcnt(0)
	v_add_f32_e32 v27, v27, v44
	ds_bpermute_b32 v44, v24, v27
	s_waitcnt lgkmcnt(0)
	v_add_f32_e32 v27, v27, v44
	ds_bpermute_b32 v44, v25, v27
	s_waitcnt lgkmcnt(0)
	v_add_f32_e32 v27, v27, v44
	v_fmamk_f32 v27, v27, 0x3a800000, v26
	v_mul_f32_e32 v44, 0x4b800000, v27
	v_cmp_gt_f32_e32 vcc, s2, v27
	s_nop 1
	v_cndmask_b32_e32 v27, v27, v44, vcc
	v_rsq_f32_e32 v27, v27
	s_nop 0
	v_mul_f32_e32 v44, 0x45800000, v27
	v_cndmask_b32_e32 v44, v27, v44, vcc
	v_pk_mul_f32 v[28:29], v[28:29], v[44:45] op_sel_hi:[1,0]
	v_pk_mul_f32 v[30:31], v[30:31], v[44:45] op_sel_hi:[1,0]
	v_pk_mul_f32 v[32:33], v[32:33], v[44:45] op_sel_hi:[1,0]
	v_pk_mul_f32 v[34:35], v[34:35], v[44:45] op_sel_hi:[1,0]
	v_pk_mul_f32 v[36:37], v[36:37], v[44:45] op_sel_hi:[1,0]
	v_pk_mul_f32 v[38:39], v[38:39], v[44:45] op_sel_hi:[1,0]
	v_pk_mul_f32 v[40:41], v[40:41], v[44:45] op_sel_hi:[1,0]
	v_pk_mul_f32 v[42:43], v[42:43], v[44:45] op_sel_hi:[1,0]
	v_pk_mul_f32 v[30:31], v[2:3], v[30:31]
	v_pk_mul_f32 v[28:29], v[0:1], v[28:29]
	v_pk_mul_f32 v[34:35], v[6:7], v[34:35]
	v_pk_mul_f32 v[32:33], v[4:5], v[32:33]
	v_pk_mul_f32 v[38:39], v[10:11], v[38:39]
	v_pk_mul_f32 v[36:37], v[8:9], v[36:37]
	v_pk_mul_f32 v[42:43], v[14:15], v[42:43]
	v_pk_mul_f32 v[40:41], v[12:13], v[40:41]
	v_cvt_pk_bf16_f32 v28, v28, v29
	v_cvt_pk_bf16_f32 v29, v30, v31
	v_cvt_pk_bf16_f32 v30, v32, v33
	v_cvt_pk_bf16_f32 v31, v34, v35
	v_cvt_pk_bf16_f32 v32, v36, v37
	v_cvt_pk_bf16_f32 v33, v38, v39
	v_cvt_pk_bf16_f32 v34, v40, v41
	v_cvt_pk_bf16_f32 v35, v42, v43
	global_store_dwordx2 v[16:17], v[28:29], off
	global_store_dwordx2 v[16:17], v[30:31], off offset:512
	global_store_dwordx2 v[16:17], v[32:33], off offset:1024
	global_store_dwordx2 v[16:17], v[34:35], off offset:1536
	v_lshl_add_u64 v[16:17], v[16:17], 0, s[0:1]
	s_cbranch_scc1 .LBB0_93

; __device__ __forceinline__ unsigned pk2(float a, float b) { f32x2_t v = {a, b}; bf16x2v_t r = __builtin_convertvector(v, bf16x2v_t); return __builtin_bit_cast(unsigned, r); }
;     __device__ __forceinline__ void operator()(const f32x4 (&acc)[2][2][4][2], const Unit& u, int wr, int wc, int fr, int fq) const {
;     ...
;             for (int m = 0; m < 4; ++m) { const int row = row0 + ai * HALF + m * 16; const size_t off = (size_t)row * ldc + col0; float s = 0.f;
; #pragma unroll
;                 for (int bj = 0; bj < 2; ++bj) { const size_t o2 = off + bj * HALF;
;                     const f32x4 v0 = *(const f32x4*)(base + o2) + acc[ai][bj][m][0], v1 = *(const f32x4*)(base + o2 + 4) + acc[ai][bj][m][1];
;                     u32x4 w; w.x = pk2(v0[0], v0[1]); w.y = pk2(v0[2], v0[3]); w.z = pk2(v1[0], v1[1]); w.w = pk2(v1[2], v1[3]); *(u32x4*)(xb + o2) = w;
;                     s += ((v0[0] * v0[0] + v0[1] * v0[1]) + (v0[2] * v0[2] + v0[3] * v0[3])) + ((v1[0] * v1[0] + v1[1] * v1[1]) + (v1[2] * v1[2] + v1[3] * v1[3])); }
;                 s += __shfl_xor(s, 16); s += __shfl_xor(s, 32);
;                 if (fq == 0) atomicAdd(rowsq + row, s);
;                 if (m & 1) asm volatile("" ::: "memory"); }
.LBB0_635:
	s_lshl_b32 s15, s24, 8
	v_mov_b32_e32 v144, v148
	v_mov_b32_e32 v155, v149
	s_add_i32 s15, s15, s34
	v_readlane_b32 s48, v255, 0
	v_add_u32_e32 v146, s15, v144
	s_lshl_b32 s15, s22, 8
	s_or_b32 s15, s15, s35
	v_lshl_add_u32 v144, v155, 3, s15
	v_ashrrev_i32_e32 v147, 31, v146
	v_ashrrev_i32_e32 v145, 31, v144
	v_lshlrev_b64 v[156:157], 10, v[146:147]
	v_lshl_add_u64 v[164:165], v[156:157], 0, v[144:145]
	v_readlane_b32 s49, v255, 1
	v_readlane_b32 s50, v255, 2
	v_readlane_b32 s51, v255, 3
	v_lshl_add_u64 v[166:167], v[164:165], 2, s[48:49]
	global_load_dwordx4 v[156:159], v[166:167], off nt
	global_load_dwordx4 v[160:163], v[166:167], off offset:16 nt
	v_lshl_add_u64 v[164:165], v[164:165], 1, s[46:47]
	v_readlane_b32 s52, v255, 4
	v_readlane_b32 s53, v255, 5
	v_readlane_b32 s54, v255, 6
	v_readlane_b32 s55, v255, 7
	v_readlane_b32 s56, v255, 8
	v_readlane_b32 s57, v255, 9
	v_readlane_b32 s58, v255, 10
	v_readlane_b32 s59, v255, 11
	v_readlane_b32 s60, v255, 12
	v_readlane_b32 s61, v255, 13
	v_readlane_b32 s62, v255, 14
	v_readlane_b32 s63, v255, 15
	s_waitcnt vmcnt(0)
	v_pk_add_f32 v[126:127], v[126:127], v[158:159]
	v_pk_add_f32 v[168:169], v[124:125], v[156:157]
	v_pk_add_f32 v[162:163], v[122:123], v[162:163]
	v_pk_add_f32 v[160:161], v[120:121], v[160:161]
	v_cvt_pk_bf16_f32 v120, v168, v169
	v_cvt_pk_bf16_f32 v121, v126, v127
	v_cvt_pk_bf16_f32 v122, v160, v161
	v_cvt_pk_bf16_f32 v123, v162, v163
	global_store_dwordx4 v[164:165], v[120:123], off
	global_load_dwordx4 v[122:125], v[166:167], off offset:512 nt
	s_nop 0
	global_load_dwordx4 v[156:159], v[166:167], off offset:528 nt
	v_and_b32_e32 v121, 64, v154
	v_mul_f32_e32 v167, v169, v169
	v_mul_f32_e32 v127, v127, v127
	v_mul_f32_e32 v161, v161, v161
	v_mul_f32_e32 v163, v163, v163
	v_xor_b32_e32 v120, 16, v154
	v_add_u32_e32 v121, 64, v121
	v_fmac_f32_e32 v167, v168, v168
	v_fmac_f32_e32 v127, v126, v126
	v_fmac_f32_e32 v161, v160, v160
	v_fmac_f32_e32 v163, v162, v162
	v_cmp_lt_i32_e32 vcc, v120, v121
	v_add_f32_e32 v126, v167, v127
	v_add_f32_e32 v127, v161, v163
	v_cndmask_b32_e32 v120, v154, v120, vcc
	v_add_f32_e32 v126, v126, v127
	v_lshlrev_b32_e32 v120, 2, v120
	v_xor_b32_e32 v166, 32, v154
	v_cmp_lt_i32_e32 vcc, v166, v121
	s_waitcnt vmcnt(1)
	v_pk_add_f32 v[118:119], v[118:119], v[124:125]
	v_pk_add_f32 v[116:117], v[116:117], v[122:123]
	s_waitcnt vmcnt(0)
	v_pk_add_f32 v[122:123], v[114:115], v[158:159]
	v_pk_add_f32 v[124:125], v[112:113], v[156:157]
	v_mul_f32_e32 v112, v117, v117
	v_mul_f32_e32 v113, v119, v119
	v_mul_f32_e32 v114, v125, v125
	v_mul_f32_e32 v115, v123, v123
	v_fmac_f32_e32 v112, v116, v116
	v_fmac_f32_e32 v113, v118, v118
	v_fmac_f32_e32 v114, v124, v124
	v_fmac_f32_e32 v115, v122, v122
	v_add_f32_e32 v112, v112, v113
	v_add_f32_e32 v113, v114, v115
	v_add_f32_e32 v112, v112, v113
	v_add_f32_e32 v112, v126, v112
	ds_bpermute_b32 v113, v120, v112
	v_cndmask_b32_e32 v114, v154, v166, vcc
	v_lshlrev_b32_e32 v114, 2, v114
	v_cmp_eq_u32_e32 vcc, 0, v155
	v_cvt_pk_bf16_f32 v116, v116, v117
	s_waitcnt lgkmcnt(0)
	v_add_f32_e32 v112, v112, v113
	ds_bpermute_b32 v113, v114, v112
	v_cvt_pk_bf16_f32 v117, v118, v119
	v_cvt_pk_bf16_f32 v118, v124, v125
	v_cvt_pk_bf16_f32 v119, v122, v123
	global_store_dwordx4 v[164:165], v[116:119], off offset:256
	s_and_saveexec_b64 s[22:23], vcc
	s_cbranch_execz .LBB0_637
	v_lshl_add_u64 v[116:117], v[146:147], 2, s[70:71]
	s_waitcnt lgkmcnt(0)
	v_add_f32_e32 v112, v112, v113
	global_atomic_add_f32 v[116:117], v112, off
.LBB0_637:
	s_or_b64 exec, exec, s[22:23]
	v_add_u32_e32 v112, 16, v146
	s_waitcnt lgkmcnt(0)
	v_ashrrev_i32_e32 v113, 31, v112
	v_lshlrev_b64 v[116:117], 10, v[112:113]
	v_readlane_b32 s48, v255, 0
	v_lshl_add_u64 v[126:127], v[116:117], 0, v[144:145]
	v_readlane_b32 s49, v255, 1
	v_readlane_b32 s50, v255, 2
	v_readlane_b32 s51, v255, 3
	v_lshl_add_u64 v[156:157], v[126:127], 2, s[48:49]
	global_load_dwordx4 v[116:119], v[156:157], off nt
	global_load_dwordx4 v[122:125], v[156:157], off offset:16 nt
	v_lshl_add_u64 v[126:127], v[126:127], 1, s[46:47]
	v_readlane_b32 s52, v255, 4
	v_readlane_b32 s53, v255, 5
	v_readlane_b32 s54, v255, 6
	v_readlane_b32 s55, v255, 7
	v_readlane_b32 s56, v255, 8
	v_readlane_b32 s57, v255, 9
	v_readlane_b32 s58, v255, 10
	v_readlane_b32 s59, v255, 11
	v_readlane_b32 s60, v255, 12
	v_readlane_b32 s61, v255, 13
	v_readlane_b32 s62, v255, 14
	v_readlane_b32 s63, v255, 15
	s_waitcnt vmcnt(1)
	v_pk_add_f32 v[118:119], v[110:111], v[118:119]
	v_pk_add_f32 v[116:117], v[108:109], v[116:117]
	s_waitcnt vmcnt(0)
	v_pk_add_f32 v[124:125], v[106:107], v[124:125]
	v_pk_add_f32 v[122:123], v[104:105], v[122:123]
	v_cvt_pk_bf16_f32 v104, v116, v117
	v_cvt_pk_bf16_f32 v105, v118, v119
	v_cvt_pk_bf16_f32 v106, v122, v123
	v_cvt_pk_bf16_f32 v107, v124, v125
	global_store_dwordx4 v[126:127], v[104:107], off
	global_load_dwordx4 v[104:107], v[156:157], off offset:512 nt
	s_nop 0
	global_load_dwordx4 v[108:111], v[156:157], off offset:528 nt
	v_mul_f32_e32 v115, v117, v117
	v_mul_f32_e32 v117, v119, v119
	v_mul_f32_e32 v119, v123, v123
	v_mul_f32_e32 v121, v125, v125
	v_fmac_f32_e32 v115, v116, v116
	v_fmac_f32_e32 v117, v118, v118
	v_fmac_f32_e32 v119, v122, v122
	v_fmac_f32_e32 v121, v124, v124
	v_add_f32_e32 v115, v115, v117
	v_add_f32_e32 v116, v119, v121
	v_add_f32_e32 v115, v115, v116
	s_waitcnt vmcnt(1)
	v_pk_add_f32 v[102:103], v[102:103], v[106:107]
	v_pk_add_f32 v[100:101], v[100:101], v[104:105]
	s_waitcnt vmcnt(0)
	v_pk_add_f32 v[104:105], v[98:99], v[110:111]
	v_pk_add_f32 v[106:107], v[96:97], v[108:109]
	v_mul_f32_e32 v96, v101, v101
	v_mul_f32_e32 v97, v103, v103
	v_mul_f32_e32 v98, v107, v107
	v_mul_f32_e32 v99, v105, v105
	v_fmac_f32_e32 v96, v100, v100
	v_fmac_f32_e32 v97, v102, v102
	v_fmac_f32_e32 v98, v106, v106
	v_fmac_f32_e32 v99, v104, v104
	v_add_f32_e32 v96, v96, v97
	v_add_f32_e32 v97, v98, v99
	v_add_f32_e32 v96, v96, v97
	v_add_f32_e32 v96, v115, v96
	ds_bpermute_b32 v97, v120, v96
	v_cvt_pk_bf16_f32 v98, v100, v101
	v_cvt_pk_bf16_f32 v99, v102, v103
	v_cvt_pk_bf16_f32 v100, v106, v107
	v_cvt_pk_bf16_f32 v101, v104, v105
	s_waitcnt lgkmcnt(0)
	v_add_f32_e32 v96, v96, v97
	ds_bpermute_b32 v97, v114, v96
	global_store_dwordx4 v[126:127], v[98:101], off offset:256
	s_and_saveexec_b64 s[22:23], vcc
	s_cbranch_execz .LBB0_639
	v_lshl_add_u64 v[98:99], v[112:113], 2, s[70:71]
	s_waitcnt lgkmcnt(0)
	v_add_f32_e32 v96, v96, v97
	global_atomic_add_f32 v[98:99], v96, off
; __device__ __forceinline__ unsigned pk2(float a, float b) { f32x2_t v = {a, b}; bf16x2v_t r = __builtin_convertvector(v, bf16x2v_t); return __builtin_bit_cast(unsigned, r); }
;     __device__ __forceinline__ void operator()(const f32x4 (&acc)[2][2][4][2], const Unit& u, int wr, int wc, int fr, int fq) const {
;     ...
;             for (int m = 0; m < 4; ++m) { const int row = row0 + ai * HALF + m * 16; const size_t off = (size_t)row * ldc + col0; float s = 0.f;
; #pragma unroll
;                 for (int bj = 0; bj < 2; ++bj) { const size_t o2 = off + bj * HALF;
;                     const f32x4 v0 = *(const f32x4*)(base + o2) + acc[ai][bj][m][0], v1 = *(const f32x4*)(base + o2 + 4) + acc[ai][bj][m][1];
;                     u32x4 w; w.x = pk2(v0[0], v0[1]); w.y = pk2(v0[2], v0[3]); w.z = pk2(v1[0], v1[1]); w.w = pk2(v1[2], v1[3]); *(u32x4*)(xb + o2) = w;
;                     s += ((v0[0] * v0[0] + v0[1] * v0[1]) + (v0[2] * v0[2] + v0[3] * v0[3])) + ((v1[0] * v1[0] + v1[1] * v1[1]) + (v1[2] * v1[2] + v1[3] * v1[3])); }
;                 s += __shfl_xor(s, 16); s += __shfl_xor(s, 32);
;                 if (fq == 0) atomicAdd(rowsq + row, s);
;                 if (m & 1) asm volatile("" ::: "memory"); }
.LBB0_639:
	s_or_b64 exec, exec, s[22:23]
	v_add_u32_e32 v96, 32, v146
	s_waitcnt lgkmcnt(0)
	v_ashrrev_i32_e32 v97, 31, v96
	v_lshlrev_b64 v[98:99], 10, v[96:97]
	v_readlane_b32 s48, v255, 0
	v_lshl_add_u64 v[106:107], v[98:99], 0, v[144:145]
	v_readlane_b32 s49, v255, 1
	v_readlane_b32 s50, v255, 2
	v_readlane_b32 s51, v255, 3
	v_lshl_add_u64 v[108:109], v[106:107], 2, s[48:49]
	global_load_dwordx4 v[98:101], v[108:109], off nt
	global_load_dwordx4 v[102:105], v[108:109], off offset:16 nt
	v_lshl_add_u64 v[106:107], v[106:107], 1, s[46:47]
	v_readlane_b32 s52, v255, 4
	v_readlane_b32 s53, v255, 5
	v_readlane_b32 s54, v255, 6
	v_readlane_b32 s55, v255, 7
	v_readlane_b32 s56, v255, 8
	v_readlane_b32 s57, v255, 9
	v_readlane_b32 s58, v255, 10
	v_readlane_b32 s59, v255, 11
	v_readlane_b32 s60, v255, 12
	v_readlane_b32 s61, v255, 13
	v_readlane_b32 s62, v255, 14
	v_readlane_b32 s63, v255, 15
	s_waitcnt vmcnt(1)
	v_pk_add_f32 v[100:101], v[94:95], v[100:101]
	v_pk_add_f32 v[98:99], v[92:93], v[98:99]
	s_waitcnt vmcnt(0)
	v_pk_add_f32 v[104:105], v[90:91], v[104:105]
	v_pk_add_f32 v[102:103], v[88:89], v[102:103]
	v_cvt_pk_bf16_f32 v88, v98, v99
	v_cvt_pk_bf16_f32 v89, v100, v101
	v_cvt_pk_bf16_f32 v90, v102, v103
	v_cvt_pk_bf16_f32 v91, v104, v105
	global_store_dwordx4 v[106:107], v[88:91], off
	global_load_dwordx4 v[88:91], v[108:109], off offset:512 nt
	s_nop 0
	global_load_dwordx4 v[92:95], v[108:109], off offset:528 nt
	v_mul_f32_e32 v99, v99, v99
	v_mul_f32_e32 v101, v101, v101
	v_mul_f32_e32 v103, v103, v103
	v_mul_f32_e32 v105, v105, v105
	v_fmac_f32_e32 v99, v98, v98
	v_fmac_f32_e32 v101, v100, v100
	v_fmac_f32_e32 v103, v102, v102
	v_fmac_f32_e32 v105, v104, v104
	v_add_f32_e32 v98, v99, v101
	v_add_f32_e32 v99, v103, v105
	v_add_f32_e32 v98, v98, v99
	s_waitcnt vmcnt(1)
	v_pk_add_f32 v[86:87], v[86:87], v[90:91]
	v_pk_add_f32 v[84:85], v[84:85], v[88:89]
	s_waitcnt vmcnt(0)
	v_pk_add_f32 v[88:89], v[82:83], v[94:95]
	v_pk_add_f32 v[90:91], v[80:81], v[92:93]
	v_mul_f32_e32 v80, v85, v85
	v_mul_f32_e32 v81, v87, v87
	v_mul_f32_e32 v82, v91, v91
	v_mul_f32_e32 v83, v89, v89
	v_fmac_f32_e32 v80, v84, v84
	v_fmac_f32_e32 v81, v86, v86
	v_fmac_f32_e32 v82, v90, v90
	v_fmac_f32_e32 v83, v88, v88
	v_add_f32_e32 v80, v80, v81
	v_add_f32_e32 v81, v82, v83
	v_add_f32_e32 v80, v80, v81
	v_add_f32_e32 v80, v98, v80
	ds_bpermute_b32 v81, v120, v80
	v_cvt_pk_bf16_f32 v82, v84, v85
	v_cvt_pk_bf16_f32 v83, v86, v87
	v_cvt_pk_bf16_f32 v84, v90, v91
	v_cvt_pk_bf16_f32 v85, v88, v89
	s_waitcnt lgkmcnt(0)
	v_add_f32_e32 v80, v80, v81
	ds_bpermute_b32 v81, v114, v80
	global_store_dwordx4 v[106:107], v[82:85], off offset:256
	s_and_saveexec_b64 s[22:23], vcc
	s_cbranch_execz .LBB0_641
	v_lshl_add_u64 v[82:83], v[96:97], 2, s[70:71]
	s_waitcnt lgkmcnt(0)
	v_add_f32_e32 v80, v80, v81
	global_atomic_add_f32 v[82:83], v80, off
.LBB0_641:
	s_or_b64 exec, exec, s[22:23]
	v_add_u32_e32 v80, 48, v146
	s_waitcnt lgkmcnt(0)
	v_ashrrev_i32_e32 v81, 31, v80
	v_lshlrev_b64 v[82:83], 10, v[80:81]
	v_readlane_b32 s48, v255, 0
	v_lshl_add_u64 v[90:91], v[82:83], 0, v[144:145]
	v_readlane_b32 s49, v255, 1
	v_readlane_b32 s50, v255, 2
	v_readlane_b32 s51, v255, 3
	v_lshl_add_u64 v[92:93], v[90:91], 2, s[48:49]
	global_load_dwordx4 v[82:85], v[92:93], off nt
	global_load_dwordx4 v[86:89], v[92:93], off offset:16 nt
	v_lshl_add_u64 v[90:91], v[90:91], 1, s[46:47]
	v_readlane_b32 s52, v255, 4
	v_readlane_b32 s53, v255, 5
	v_readlane_b32 s54, v255, 6
	v_readlane_b32 s55, v255, 7
	v_readlane_b32 s56, v255, 8
	v_readlane_b32 s57, v255, 9
	v_readlane_b32 s58, v255, 10
	v_readlane_b32 s59, v255, 11
	v_readlane_b32 s60, v255, 12
	v_readlane_b32 s61, v255, 13
	v_readlane_b32 s62, v255, 14
	v_readlane_b32 s63, v255, 15
	s_waitcnt vmcnt(1)
	v_pk_add_f32 v[84:85], v[78:79], v[84:85]
	v_pk_add_f32 v[82:83], v[76:77], v[82:83]
	s_waitcnt vmcnt(0)
	v_pk_add_f32 v[88:89], v[74:75], v[88:89]
	v_pk_add_f32 v[86:87], v[72:73], v[86:87]
	v_cvt_pk_bf16_f32 v72, v82, v83
	v_cvt_pk_bf16_f32 v73, v84, v85
	v_cvt_pk_bf16_f32 v74, v86, v87
	v_cvt_pk_bf16_f32 v75, v88, v89
	global_store_dwordx4 v[90:91], v[72:75], off
	global_load_dwordx4 v[72:75], v[92:93], off offset:512 nt
	s_nop 0
	global_load_dwordx4 v[76:79], v[92:93], off offset:528 nt
	v_mul_f32_e32 v83, v83, v83
	v_mul_f32_e32 v85, v85, v85
	v_mul_f32_e32 v87, v87, v87
	v_mul_f32_e32 v89, v89, v89
	v_fmac_f32_e32 v83, v82, v82
	v_fmac_f32_e32 v85, v84, v84
	v_fmac_f32_e32 v87, v86, v86
	v_fmac_f32_e32 v89, v88, v88
	v_add_f32_e32 v82, v83, v85
	v_add_f32_e32 v83, v87, v89
	v_add_f32_e32 v82, v82, v83
	s_waitcnt vmcnt(1)
	v_pk_add_f32 v[70:71], v[70:71], v[74:75]
	v_pk_add_f32 v[68:69], v[68:69], v[72:73]
	s_waitcnt vmcnt(0)
	v_pk_add_f32 v[72:73], v[66:67], v[78:79]
	v_pk_add_f32 v[74:75], v[64:65], v[76:77]
	v_mul_f32_e32 v64, v69, v69
	v_mul_f32_e32 v65, v71, v71
	v_mul_f32_e32 v66, v75, v75
	v_mul_f32_e32 v67, v73, v73
	v_fmac_f32_e32 v64, v68, v68
	v_fmac_f32_e32 v65, v70, v70
	v_fmac_f32_e32 v66, v74, v74
	v_fmac_f32_e32 v67, v72, v72
	v_add_f32_e32 v64, v64, v65
	v_add_f32_e32 v65, v66, v67
	v_add_f32_e32 v64, v64, v65
	v_add_f32_e32 v64, v82, v64
	ds_bpermute_b32 v65, v120, v64
	v_cvt_pk_bf16_f32 v66, v68, v69
	v_cvt_pk_bf16_f32 v67, v70, v71
	v_cvt_pk_bf16_f32 v68, v74, v75
	v_cvt_pk_bf16_f32 v69, v72, v73
	s_waitcnt lgkmcnt(0)
	v_add_f32_e32 v64, v64, v65
	ds_bpermute_b32 v65, v114, v64
	global_store_dwordx4 v[90:91], v[66:69], off offset:256
	s_and_saveexec_b64 s[22:23], vcc
	s_cbranch_execz .LBB0_643
	v_lshl_add_u64 v[66:67], v[80:81], 2, s[70:71]
	s_waitcnt lgkmcnt(0)
	v_add_f32_e32 v64, v64, v65
	global_atomic_add_f32 v[66:67], v64, off
; __device__ __forceinline__ unsigned pk2(float a, float b) { f32x2_t v = {a, b}; bf16x2v_t r = __builtin_convertvector(v, bf16x2v_t); return __builtin_bit_cast(unsigned, r); }
;     __device__ __forceinline__ void operator()(const f32x4 (&acc)[2][2][4][2], const Unit& u, int wr, int wc, int fr, int fq) const {
;     ...
;             for (int m = 0; m < 4; ++m) { const int row = row0 + ai * HALF + m * 16; const size_t off = (size_t)row * ldc + col0; float s = 0.f;
; #pragma unroll
;                 for (int bj = 0; bj < 2; ++bj) { const size_t o2 = off + bj * HALF;
;                     const f32x4 v0 = *(const f32x4*)(base + o2) + acc[ai][bj][m][0], v1 = *(const f32x4*)(base + o2 + 4) + acc[ai][bj][m][1];
;                     u32x4 w; w.x = pk2(v0[0], v0[1]); w.y = pk2(v0[2], v0[3]); w.z = pk2(v1[0], v1[1]); w.w = pk2(v1[2], v1[3]); *(u32x4*)(xb + o2) = w;
;                     s += ((v0[0] * v0[0] + v0[1] * v0[1]) + (v0[2] * v0[2] + v0[3] * v0[3])) + ((v1[0] * v1[0] + v1[1] * v1[1]) + (v1[2] * v1[2] + v1[3] * v1[3])); }
;                 s += __shfl_xor(s, 16); s += __shfl_xor(s, 32);
;                 if (fq == 0) atomicAdd(rowsq + row, s);
;                 if (m & 1) asm volatile("" ::: "memory"); }
.LBB0_643:
	s_or_b64 exec, exec, s[22:23]
	v_add_u32_e32 v64, 0x80, v146
	s_waitcnt lgkmcnt(0)
	v_ashrrev_i32_e32 v65, 31, v64
	v_lshlrev_b64 v[66:67], 10, v[64:65]
	v_readlane_b32 s48, v255, 0
	v_lshl_add_u64 v[74:75], v[66:67], 0, v[144:145]
	v_readlane_b32 s49, v255, 1
	v_readlane_b32 s50, v255, 2
	v_readlane_b32 s51, v255, 3
	v_lshl_add_u64 v[76:77], v[74:75], 2, s[48:49]
	global_load_dwordx4 v[66:69], v[76:77], off nt
	global_load_dwordx4 v[70:73], v[76:77], off offset:16 nt
	v_lshl_add_u64 v[74:75], v[74:75], 1, s[46:47]
	v_readlane_b32 s52, v255, 4
	v_readlane_b32 s53, v255, 5
	v_readlane_b32 s54, v255, 6
	v_readlane_b32 s55, v255, 7
	v_readlane_b32 s56, v255, 8
	v_readlane_b32 s57, v255, 9
	v_readlane_b32 s58, v255, 10
	v_readlane_b32 s59, v255, 11
	v_readlane_b32 s60, v255, 12
	v_readlane_b32 s61, v255, 13
	v_readlane_b32 s62, v255, 14
	v_readlane_b32 s63, v255, 15
	s_waitcnt vmcnt(1)
	v_pk_add_f32 v[68:69], v[62:63], v[68:69]
	v_pk_add_f32 v[66:67], v[60:61], v[66:67]
	s_waitcnt vmcnt(0)
	v_pk_add_f32 v[72:73], v[58:59], v[72:73]
	v_pk_add_f32 v[70:71], v[56:57], v[70:71]
	v_cvt_pk_bf16_f32 v56, v66, v67
	v_cvt_pk_bf16_f32 v57, v68, v69
	v_cvt_pk_bf16_f32 v58, v70, v71
	v_cvt_pk_bf16_f32 v59, v72, v73
	global_store_dwordx4 v[74:75], v[56:59], off
	global_load_dwordx4 v[56:59], v[76:77], off offset:512 nt
	s_nop 0
	global_load_dwordx4 v[60:63], v[76:77], off offset:528 nt
	v_mul_f32_e32 v67, v67, v67
	v_mul_f32_e32 v69, v69, v69
	v_mul_f32_e32 v71, v71, v71
	v_mul_f32_e32 v73, v73, v73
	v_fmac_f32_e32 v67, v66, v66
	v_fmac_f32_e32 v69, v68, v68
	v_fmac_f32_e32 v71, v70, v70
	v_fmac_f32_e32 v73, v72, v72
	v_add_f32_e32 v66, v67, v69
	v_add_f32_e32 v67, v71, v73
	v_add_f32_e32 v66, v66, v67
	s_waitcnt vmcnt(1)
	v_pk_add_f32 v[54:55], v[54:55], v[58:59]
	v_pk_add_f32 v[52:53], v[52:53], v[56:57]
	s_waitcnt vmcnt(0)
	v_pk_add_f32 v[56:57], v[50:51], v[62:63]
	v_pk_add_f32 v[58:59], v[48:49], v[60:61]
	v_mul_f32_e32 v48, v53, v53
	v_mul_f32_e32 v49, v55, v55
	v_mul_f32_e32 v50, v59, v59
	v_mul_f32_e32 v51, v57, v57
	v_fmac_f32_e32 v48, v52, v52
	v_fmac_f32_e32 v49, v54, v54
	v_fmac_f32_e32 v50, v58, v58
	v_fmac_f32_e32 v51, v56, v56
	v_add_f32_e32 v48, v48, v49
	v_add_f32_e32 v49, v50, v51
	v_add_f32_e32 v48, v48, v49
	v_add_f32_e32 v48, v66, v48
	ds_bpermute_b32 v49, v120, v48
	v_cvt_pk_bf16_f32 v50, v52, v53
	v_cvt_pk_bf16_f32 v51, v54, v55
	v_cvt_pk_bf16_f32 v52, v58, v59
	v_cvt_pk_bf16_f32 v53, v56, v57
	s_waitcnt lgkmcnt(0)
	v_add_f32_e32 v48, v48, v49
	ds_bpermute_b32 v49, v114, v48
	global_store_dwordx4 v[74:75], v[50:53], off offset:256
	s_and_saveexec_b64 s[22:23], vcc
	s_cbranch_execz .LBB0_645
	v_lshl_add_u64 v[50:51], v[64:65], 2, s[70:71]
	s_waitcnt lgkmcnt(0)
	v_add_f32_e32 v48, v48, v49
	global_atomic_add_f32 v[50:51], v48, off
.LBB0_645:
	s_or_b64 exec, exec, s[22:23]
	v_add_u32_e32 v48, 0x90, v146
	s_waitcnt lgkmcnt(0)
	v_ashrrev_i32_e32 v49, 31, v48
	v_lshlrev_b64 v[50:51], 10, v[48:49]
	v_readlane_b32 s48, v255, 0
	v_lshl_add_u64 v[58:59], v[50:51], 0, v[144:145]
	v_readlane_b32 s49, v255, 1
	v_readlane_b32 s50, v255, 2
	v_readlane_b32 s51, v255, 3
	v_lshl_add_u64 v[60:61], v[58:59], 2, s[48:49]
	global_load_dwordx4 v[50:53], v[60:61], off nt
	global_load_dwordx4 v[54:57], v[60:61], off offset:16 nt
	v_lshl_add_u64 v[58:59], v[58:59], 1, s[46:47]
	v_readlane_b32 s52, v255, 4
	v_readlane_b32 s53, v255, 5
	v_readlane_b32 s54, v255, 6
	v_readlane_b32 s55, v255, 7
	v_readlane_b32 s56, v255, 8
	v_readlane_b32 s57, v255, 9
	v_readlane_b32 s58, v255, 10
	v_readlane_b32 s59, v255, 11
	v_readlane_b32 s60, v255, 12
	v_readlane_b32 s61, v255, 13
	v_readlane_b32 s62, v255, 14
	v_readlane_b32 s63, v255, 15
	s_waitcnt vmcnt(1)
	v_pk_add_f32 v[52:53], v[46:47], v[52:53]
	v_pk_add_f32 v[50:51], v[44:45], v[50:51]
	s_waitcnt vmcnt(0)
	v_pk_add_f32 v[56:57], v[42:43], v[56:57]
	v_pk_add_f32 v[54:55], v[40:41], v[54:55]
	v_cvt_pk_bf16_f32 v40, v50, v51
	v_cvt_pk_bf16_f32 v41, v52, v53
	v_cvt_pk_bf16_f32 v42, v54, v55
	v_cvt_pk_bf16_f32 v43, v56, v57
	global_store_dwordx4 v[58:59], v[40:43], off
	global_load_dwordx4 v[40:43], v[60:61], off offset:512 nt
	s_nop 0
	global_load_dwordx4 v[44:47], v[60:61], off offset:528 nt
	v_mul_f32_e32 v51, v51, v51
	v_mul_f32_e32 v53, v53, v53
	v_mul_f32_e32 v55, v55, v55
	v_mul_f32_e32 v57, v57, v57
	v_fmac_f32_e32 v51, v50, v50
	v_fmac_f32_e32 v53, v52, v52
	v_fmac_f32_e32 v55, v54, v54
	v_fmac_f32_e32 v57, v56, v56
	v_add_f32_e32 v50, v51, v53
	v_add_f32_e32 v51, v55, v57
	v_add_f32_e32 v50, v50, v51
	s_waitcnt vmcnt(1)
	v_pk_add_f32 v[38:39], v[38:39], v[42:43]
	v_pk_add_f32 v[36:37], v[36:37], v[40:41]
	s_waitcnt vmcnt(0)
	v_pk_add_f32 v[40:41], v[34:35], v[46:47]
	v_pk_add_f32 v[42:43], v[32:33], v[44:45]
	v_mul_f32_e32 v32, v37, v37
	v_mul_f32_e32 v33, v39, v39
	v_mul_f32_e32 v34, v43, v43
	v_mul_f32_e32 v35, v41, v41
	v_fmac_f32_e32 v32, v36, v36
	v_fmac_f32_e32 v33, v38, v38
	v_fmac_f32_e32 v34, v42, v42
	v_fmac_f32_e32 v35, v40, v40
	v_add_f32_e32 v32, v32, v33
	v_add_f32_e32 v33, v34, v35
	v_add_f32_e32 v32, v32, v33
	v_add_f32_e32 v32, v50, v32
	ds_bpermute_b32 v33, v120, v32
	v_cvt_pk_bf16_f32 v34, v36, v37
	v_cvt_pk_bf16_f32 v35, v38, v39
	v_cvt_pk_bf16_f32 v36, v42, v43
	v_cvt_pk_bf16_f32 v37, v40, v41
	s_waitcnt lgkmcnt(0)
	v_add_f32_e32 v32, v32, v33
	ds_bpermute_b32 v33, v114, v32
	global_store_dwordx4 v[58:59], v[34:37], off offset:256
	s_and_saveexec_b64 s[22:23], vcc
	s_cbranch_execz .LBB0_647
	v_lshl_add_u64 v[34:35], v[48:49], 2, s[70:71]
	s_waitcnt lgkmcnt(0)
	v_add_f32_e32 v32, v32, v33
	global_atomic_add_f32 v[34:35], v32, off
; __device__ __forceinline__ unsigned pk2(float a, float b) { f32x2_t v = {a, b}; bf16x2v_t r = __builtin_convertvector(v, bf16x2v_t); return __builtin_bit_cast(unsigned, r); }
;     __device__ __forceinline__ void operator()(const f32x4 (&acc)[2][2][4][2], const Unit& u, int wr, int wc, int fr, int fq) const {
;     ...
;             for (int m = 0; m < 4; ++m) { const int row = row0 + ai * HALF + m * 16; const size_t off = (size_t)row * ldc + col0; float s = 0.f;
; #pragma unroll
;                 for (int bj = 0; bj < 2; ++bj) { const size_t o2 = off + bj * HALF;
;                     const f32x4 v0 = *(const f32x4*)(base + o2) + acc[ai][bj][m][0], v1 = *(const f32x4*)(base + o2 + 4) + acc[ai][bj][m][1];
;                     u32x4 w; w.x = pk2(v0[0], v0[1]); w.y = pk2(v0[2], v0[3]); w.z = pk2(v1[0], v1[1]); w.w = pk2(v1[2], v1[3]); *(u32x4*)(xb + o2) = w;
;                     s += ((v0[0] * v0[0] + v0[1] * v0[1]) + (v0[2] * v0[2] + v0[3] * v0[3])) + ((v1[0] * v1[0] + v1[1] * v1[1]) + (v1[2] * v1[2] + v1[3] * v1[3])); }
;                 s += __shfl_xor(s, 16); s += __shfl_xor(s, 32);
;                 if (fq == 0) atomicAdd(rowsq + row, s);
;                 if (m & 1) asm volatile("" ::: "memory"); }
.LBB0_647:
	s_or_b64 exec, exec, s[22:23]
	v_add_u32_e32 v32, 0xa0, v146
	s_waitcnt lgkmcnt(0)
	v_ashrrev_i32_e32 v33, 31, v32
	v_lshlrev_b64 v[34:35], 10, v[32:33]
	v_readlane_b32 s48, v255, 0
	v_lshl_add_u64 v[42:43], v[34:35], 0, v[144:145]
	v_readlane_b32 s49, v255, 1
	v_readlane_b32 s50, v255, 2
	v_readlane_b32 s51, v255, 3
	v_lshl_add_u64 v[44:45], v[42:43], 2, s[48:49]
	global_load_dwordx4 v[34:37], v[44:45], off nt
	global_load_dwordx4 v[38:41], v[44:45], off offset:16 nt
	v_lshl_add_u64 v[42:43], v[42:43], 1, s[46:47]
	v_readlane_b32 s52, v255, 4
	v_readlane_b32 s53, v255, 5
	v_readlane_b32 s54, v255, 6
	v_readlane_b32 s55, v255, 7
	v_readlane_b32 s56, v255, 8
	v_readlane_b32 s57, v255, 9
	v_readlane_b32 s58, v255, 10
	v_readlane_b32 s59, v255, 11
	v_readlane_b32 s60, v255, 12
	v_readlane_b32 s61, v255, 13
	v_readlane_b32 s62, v255, 14
	v_readlane_b32 s63, v255, 15
	s_waitcnt vmcnt(1)
	v_pk_add_f32 v[36:37], v[30:31], v[36:37]
	v_pk_add_f32 v[34:35], v[28:29], v[34:35]
	s_waitcnt vmcnt(0)
	v_pk_add_f32 v[40:41], v[26:27], v[40:41]
	v_pk_add_f32 v[38:39], v[24:25], v[38:39]
	v_cvt_pk_bf16_f32 v24, v34, v35
	v_cvt_pk_bf16_f32 v25, v36, v37
	v_cvt_pk_bf16_f32 v26, v38, v39
	v_cvt_pk_bf16_f32 v27, v40, v41
	global_store_dwordx4 v[42:43], v[24:27], off
	global_load_dwordx4 v[24:27], v[44:45], off offset:512 nt
	s_nop 0
	global_load_dwordx4 v[28:31], v[44:45], off offset:528 nt
	v_mul_f32_e32 v35, v35, v35
	v_mul_f32_e32 v37, v37, v37
	v_mul_f32_e32 v39, v39, v39
	v_mul_f32_e32 v41, v41, v41
	v_fmac_f32_e32 v35, v34, v34
	v_fmac_f32_e32 v37, v36, v36
	v_fmac_f32_e32 v39, v38, v38
	v_fmac_f32_e32 v41, v40, v40
	v_add_f32_e32 v34, v35, v37
	v_add_f32_e32 v35, v39, v41
	v_add_f32_e32 v34, v34, v35
	s_waitcnt vmcnt(1)
	v_pk_add_f32 v[22:23], v[22:23], v[26:27]
	v_pk_add_f32 v[20:21], v[20:21], v[24:25]
	s_waitcnt vmcnt(0)
	v_pk_add_f32 v[24:25], v[18:19], v[30:31]
	v_pk_add_f32 v[26:27], v[16:17], v[28:29]
	v_mul_f32_e32 v16, v21, v21
	v_mul_f32_e32 v17, v23, v23
	v_mul_f32_e32 v18, v27, v27
	v_mul_f32_e32 v19, v25, v25
	v_fmac_f32_e32 v16, v20, v20
	v_fmac_f32_e32 v17, v22, v22
	v_fmac_f32_e32 v18, v26, v26
	v_fmac_f32_e32 v19, v24, v24
	v_add_f32_e32 v16, v16, v17
	v_add_f32_e32 v17, v18, v19
	v_add_f32_e32 v16, v16, v17
	v_add_f32_e32 v16, v34, v16
	ds_bpermute_b32 v17, v120, v16
	v_cvt_pk_bf16_f32 v18, v20, v21
	v_cvt_pk_bf16_f32 v19, v22, v23
	v_cvt_pk_bf16_f32 v20, v26, v27
	v_cvt_pk_bf16_f32 v21, v24, v25
	s_waitcnt lgkmcnt(0)
	v_add_f32_e32 v16, v16, v17
	ds_bpermute_b32 v17, v114, v16
	global_store_dwordx4 v[42:43], v[18:21], off offset:256
	s_and_saveexec_b64 s[22:23], vcc
	s_cbranch_execz .LBB0_649
	v_lshl_add_u64 v[18:19], v[32:33], 2, s[70:71]
	s_waitcnt lgkmcnt(0)
	v_add_f32_e32 v16, v16, v17
	global_atomic_add_f32 v[18:19], v16, off
.LBB0_649:
	s_or_b64 exec, exec, s[22:23]
	v_add_u32_e32 v16, 0xb0, v146
	s_waitcnt lgkmcnt(0)
	v_ashrrev_i32_e32 v17, 31, v16
	v_lshlrev_b64 v[18:19], 10, v[16:17]
	v_readlane_b32 s48, v255, 0
	v_lshl_add_u64 v[26:27], v[18:19], 0, v[144:145]
	v_readlane_b32 s49, v255, 1
	v_readlane_b32 s50, v255, 2
	v_readlane_b32 s51, v255, 3
	v_lshl_add_u64 v[28:29], v[26:27], 2, s[48:49]
	global_load_dwordx4 v[18:21], v[28:29], off nt
	global_load_dwordx4 v[22:25], v[28:29], off offset:16 nt
	v_lshl_add_u64 v[26:27], v[26:27], 1, s[46:47]
	v_readlane_b32 s52, v255, 4
	v_readlane_b32 s53, v255, 5
	v_readlane_b32 s54, v255, 6
	v_readlane_b32 s55, v255, 7
	v_readlane_b32 s56, v255, 8
	v_readlane_b32 s57, v255, 9
	v_readlane_b32 s58, v255, 10
	v_readlane_b32 s59, v255, 11
	v_readlane_b32 s60, v255, 12
	v_readlane_b32 s61, v255, 13
	v_readlane_b32 s62, v255, 14
	v_readlane_b32 s63, v255, 15
	s_waitcnt vmcnt(1)
	v_pk_add_f32 v[20:21], v[14:15], v[20:21]
	v_pk_add_f32 v[18:19], v[12:13], v[18:19]
	s_waitcnt vmcnt(0)
	v_pk_add_f32 v[24:25], v[10:11], v[24:25]
	v_pk_add_f32 v[22:23], v[8:9], v[22:23]
	v_cvt_pk_bf16_f32 v8, v18, v19
	v_cvt_pk_bf16_f32 v9, v20, v21
	v_cvt_pk_bf16_f32 v10, v22, v23
	v_cvt_pk_bf16_f32 v11, v24, v25
	global_store_dwordx4 v[26:27], v[8:11], off
	global_load_dwordx4 v[8:11], v[28:29], off offset:512 nt
	s_nop 0
	global_load_dwordx4 v[12:15], v[28:29], off offset:528 nt
	v_mul_f32_e32 v19, v19, v19
	v_mul_f32_e32 v21, v21, v21
	v_mul_f32_e32 v23, v23, v23
	v_mul_f32_e32 v25, v25, v25
	v_fmac_f32_e32 v19, v18, v18
	v_fmac_f32_e32 v21, v20, v20
	v_fmac_f32_e32 v23, v22, v22
	v_fmac_f32_e32 v25, v24, v24
	v_add_f32_e32 v18, v19, v21
	v_add_f32_e32 v19, v23, v25
	v_add_f32_e32 v18, v18, v19
	s_waitcnt vmcnt(1)
	v_pk_add_f32 v[6:7], v[6:7], v[10:11]
	v_pk_add_f32 v[4:5], v[4:5], v[8:9]
	s_waitcnt vmcnt(0)
	v_pk_add_f32 v[8:9], v[2:3], v[14:15]
	v_pk_add_f32 v[10:11], v[0:1], v[12:13]
	v_mul_f32_e32 v0, v5, v5
	v_mul_f32_e32 v1, v7, v7
	v_mul_f32_e32 v2, v11, v11
	v_mul_f32_e32 v3, v9, v9
	v_fmac_f32_e32 v0, v4, v4
	v_fmac_f32_e32 v1, v6, v6
	v_fmac_f32_e32 v2, v10, v10
	v_fmac_f32_e32 v3, v8, v8
	v_add_f32_e32 v0, v0, v1
	v_add_f32_e32 v1, v2, v3
	v_add_f32_e32 v0, v0, v1
	v_add_f32_e32 v0, v18, v0
	ds_bpermute_b32 v1, v120, v0
	v_cvt_pk_bf16_f32 v2, v4, v5
	v_cvt_pk_bf16_f32 v3, v6, v7
	v_cvt_pk_bf16_f32 v4, v10, v11
	v_cvt_pk_bf16_f32 v5, v8, v9
	s_waitcnt lgkmcnt(0)
	v_add_f32_e32 v0, v0, v1
	ds_bpermute_b32 v1, v114, v0
	global_store_dwordx4 v[26:27], v[2:5], off offset:256
	s_and_saveexec_b64 s[22:23], vcc
	s_cbranch_execz .LBB0_651
	v_lshl_add_u64 v[2:3], v[16:17], 2, s[70:71]
	s_waitcnt lgkmcnt(0)
	v_add_f32_e32 v0, v0, v1
	global_atomic_add_f32 v[2:3], v0, off

;     __device__ __forceinline__ void operator()(const f32x4 (&acc)[2][2][4][2], const Unit& u, int wr, int wc, int fr, int fq) const {
;     ...
;             for (int m = 0; m < 4; ++m) { const int row = row0 + ai * HALF + m * 16; const size_t off = (size_t)row * ldc + col0;
;                 const float nrl = -1.4426950408889634f * __builtin_amdgcn_rsqf(__hip_atomic_load(rowsq + row, __ATOMIC_RELAXED, __HIP_MEMORY_SCOPE_AGENT) * (1.f / (float)ldc) + eps);
; #pragma unroll
;                 for (int bj = 0; bj < 2; ++bj) { const size_t o2 = off + bj * HALF; const u32x4 xw = *(const u32x4*)(xb + o2), g = *(const u32x4*)(pl + o2);
;                     f32x4 b0, b1, p0, p1;
;                     b0[0] = __uint_as_float(xw.x << 16); b0[1] = __uint_as_float(xw.x & 0xffff0000u); b0[2] = __uint_as_float(xw.y << 16); b0[3] = __uint_as_float(xw.y & 0xffff0000u);
;                     b1[0] = __uint_as_float(xw.z << 16); b1[1] = __uint_as_float(xw.z & 0xffff0000u); b1[2] = __uint_as_float(xw.w << 16); b1[3] = __uint_as_float(xw.w & 0xffff0000u);
;                     p0[0] = __uint_as_float(g.x << 16); p0[1] = __uint_as_float(g.x & 0xffff0000u); p0[2] = __uint_as_float(g.y << 16); p0[3] = __uint_as_float(g.y & 0xffff0000u);
;                     p1[0] = __uint_as_float(g.z << 16); p1[1] = __uint_as_float(g.z & 0xffff0000u); p1[2] = __uint_as_float(g.w << 16); p1[3] = __uint_as_float(g.w & 0xffff0000u);
;                     f32x4 s0, s1;
; #pragma unroll
;                     for (int e = 0; e < 4; ++e) { s0[e] = __builtin_amdgcn_rcpf(1.f + __builtin_amdgcn_exp2f(nrl * acc[ai][bj][m][0][e])); s1[e] = __builtin_amdgcn_rcpf(1.f + __builtin_amdgcn_exp2f(nrl * acc[ai][bj][m][1][e])); }
;                     *(f32x4*)(out + o2) = b0 + s0 * p0; *(f32x4*)(out + o2 + 4) = b1 + s1 * p1; }
.LBB0_727:
	s_lshl_b32 s8, s38, 8
	s_add_i32 s8, s8, s55
	s_lshl_b32 s2, s2, 8
	s_or_b32 s2, s2, s56
	v_add_u32_e32 v144, s8, v148
	v_lshl_add_u32 v145, v149, 3, s2
	v_lshl_add_u32 v146, v144, 10, v145
	v_lshlrev_b32_e32 v156, 2, v144
	v_lshlrev_b32_e32 v147, 1, v146
	v_lshlrev_b32_e32 v155, 2, v146
	s_andn2_b64 vcc, exec, s[0:1]
	s_mov_b64 s[0:1], -1
	s_mov_b64 s[72:73], s[46:47]
	s_mov_b64 s[74:75], s[6:7]
	global_load_dword v198, v156, s[70:71] sc1
	global_load_dwordx4 v[182:185], v147, s[72:73]
	global_load_dwordx4 v[190:193], v147, s[74:75]
	global_load_dwordx4 v[186:189], v147, s[72:73] offset:256
	global_load_dwordx4 v[194:197], v147, s[74:75] offset:256
	s_add_u32 s72, s46, 0x8000
	s_addc_u32 s73, s47, 0
	s_add_u32 s74, s6, 0x8000
	s_addc_u32 s75, s7, 0
	global_load_dword v216, v156, s[70:71] offset:64 sc1
	global_load_dwordx4 v[200:203], v147, s[72:73]
	global_load_dwordx4 v[208:211], v147, s[74:75]
	global_load_dwordx4 v[204:207], v147, s[72:73] offset:256
	global_load_dwordx4 v[212:215], v147, s[74:75] offset:256
	s_add_u32 s72, s46, 0x10000
	s_addc_u32 s73, s47, 0
	s_add_u32 s74, s6, 0x10000
	s_addc_u32 s75, s7, 0
	global_load_dword v234, v156, s[70:71] offset:128 sc1
	global_load_dwordx4 v[218:221], v147, s[72:73]
	global_load_dwordx4 v[226:229], v147, s[74:75]
	global_load_dwordx4 v[222:225], v147, s[72:73] offset:256
	global_load_dwordx4 v[230:233], v147, s[74:75] offset:256
	s_add_u32 s72, s46, 0x18000
	s_addc_u32 s73, s47, 0
	s_add_u32 s74, s6, 0x18000
	s_addc_u32 s75, s7, 0
	global_load_dword v252, v156, s[70:71] offset:192 sc1
	global_load_dwordx4 v[236:239], v147, s[72:73]
	global_load_dwordx4 v[244:247], v147, s[74:75]
	global_load_dwordx4 v[240:243], v147, s[72:73] offset:256
	global_load_dwordx4 v[248:251], v147, s[74:75] offset:256
	s_waitcnt vmcnt(15)
	v_fmamk_f32 v157, v198, 0x3a800000, v154
	v_rsq_f32_e32 v157, v157
	s_mov_b64 s[76:77], s[80:81]
	s_nop 0
	v_mul_f32_e32 v157, 0xbfb8aa3b, v157
	v_mul_f32_e32 v120, v120, v157
	v_mul_f32_e32 v121, v121, v157
	v_mul_f32_e32 v122, v122, v157
	v_mul_f32_e32 v123, v123, v157
	v_mul_f32_e32 v124, v124, v157
	v_mul_f32_e32 v125, v125, v157
	v_mul_f32_e32 v126, v126, v157
	v_mul_f32_e32 v127, v127, v157
	v_exp_f32_e32 v120, v120
	v_exp_f32_e32 v121, v121
	v_exp_f32_e32 v122, v122
	v_exp_f32_e32 v123, v123
	v_exp_f32_e32 v124, v124
	v_exp_f32_e32 v125, v125
	v_exp_f32_e32 v126, v126
	v_exp_f32_e32 v127, v127
	v_add_f32_e32 v120, 1.0, v120
	v_add_f32_e32 v121, 1.0, v121
	v_add_f32_e32 v122, 1.0, v122
	v_add_f32_e32 v123, 1.0, v123
	v_add_f32_e32 v124, 1.0, v124
	v_add_f32_e32 v125, 1.0, v125
	v_add_f32_e32 v126, 1.0, v126
	v_add_f32_e32 v127, 1.0, v127
	v_rcp_f32_e32 v120, v120
	v_rcp_f32_e32 v121, v121
	v_rcp_f32_e32 v122, v122
	v_rcp_f32_e32 v123, v123
	v_rcp_f32_e32 v124, v124
	v_rcp_f32_e32 v125, v125
	v_rcp_f32_e32 v126, v126
	v_rcp_f32_e32 v127, v127
	v_lshlrev_b32_e32 v158, 16, v182
	v_and_b32_e32 v159, 0xffff0000, v182
	v_lshlrev_b32_e32 v166, 16, v190
	v_and_b32_e32 v167, 0xffff0000, v190
	v_lshlrev_b32_e32 v160, 16, v183
	v_and_b32_e32 v161, 0xffff0000, v183
	v_lshlrev_b32_e32 v168, 16, v191
	v_and_b32_e32 v169, 0xffff0000, v191
	v_lshlrev_b32_e32 v162, 16, v184
	v_and_b32_e32 v163, 0xffff0000, v184
	v_lshlrev_b32_e32 v170, 16, v192
	v_and_b32_e32 v171, 0xffff0000, v192
	v_lshlrev_b32_e32 v164, 16, v185
	v_and_b32_e32 v165, 0xffff0000, v185
	v_lshlrev_b32_e32 v172, 16, v193
	v_and_b32_e32 v173, 0xffff0000, v193
	v_pk_fma_f32 v[124:125], v[124:125], v[166:167], v[158:159]
	v_pk_fma_f32 v[126:127], v[126:127], v[168:169], v[160:161]
	v_pk_fma_f32 v[120:121], v[120:121], v[170:171], v[162:163]
	v_pk_fma_f32 v[122:123], v[122:123], v[172:173], v[164:165]
	global_store_dwordx4 v155, v[124:127], s[76:77] nt
	global_store_dwordx4 v155, v[120:123], s[76:77] offset:16 nt
	v_mul_f32_e32 v112, v112, v157
	v_mul_f32_e32 v113, v113, v157
	v_mul_f32_e32 v114, v114, v157
	v_mul_f32_e32 v115, v115, v157
	v_mul_f32_e32 v116, v116, v157
	v_mul_f32_e32 v117, v117, v157
	v_mul_f32_e32 v118, v118, v157
	v_mul_f32_e32 v119, v119, v157
	v_exp_f32_e32 v112, v112
	v_exp_f32_e32 v113, v113
	v_exp_f32_e32 v114, v114
	v_exp_f32_e32 v115, v115
	v_exp_f32_e32 v116, v116
	v_exp_f32_e32 v117, v117
	v_exp_f32_e32 v118, v118
	v_exp_f32_e32 v119, v119
	v_add_f32_e32 v112, 1.0, v112
	v_add_f32_e32 v113, 1.0, v113
	v_add_f32_e32 v114, 1.0, v114
	v_add_f32_e32 v115, 1.0, v115
	v_add_f32_e32 v116, 1.0, v116
	v_add_f32_e32 v117, 1.0, v117
	v_add_f32_e32 v118, 1.0, v118
	v_add_f32_e32 v119, 1.0, v119
	v_rcp_f32_e32 v112, v112
	v_rcp_f32_e32 v113, v113
	v_rcp_f32_e32 v114, v114
	v_rcp_f32_e32 v115, v115
	v_rcp_f32_e32 v116, v116
	v_rcp_f32_e32 v117, v117
	v_rcp_f32_e32 v118, v118
	v_rcp_f32_e32 v119, v119
	v_lshlrev_b32_e32 v158, 16, v186
	v_and_b32_e32 v159, 0xffff0000, v186
	v_lshlrev_b32_e32 v166, 16, v194
	v_and_b32_e32 v167, 0xffff0000, v194
	v_lshlrev_b32_e32 v160, 16, v187
	v_and_b32_e32 v161, 0xffff0000, v187
	v_lshlrev_b32_e32 v168, 16, v195
	v_and_b32_e32 v169, 0xffff0000, v195
	v_lshlrev_b32_e32 v162, 16, v188
	v_and_b32_e32 v163, 0xffff0000, v188
	v_lshlrev_b32_e32 v170, 16, v196
	v_and_b32_e32 v171, 0xffff0000, v196
	v_lshlrev_b32_e32 v164, 16, v189
	v_and_b32_e32 v165, 0xffff0000, v189
	v_lshlrev_b32_e32 v172, 16, v197
	v_and_b32_e32 v173, 0xffff0000, v197
	v_pk_fma_f32 v[116:117], v[116:117], v[166:167], v[158:159]
	v_pk_fma_f32 v[118:119], v[118:119], v[168:169], v[160:161]
	v_pk_fma_f32 v[112:113], v[112:113], v[170:171], v[162:163]
	v_pk_fma_f32 v[114:115], v[114:115], v[172:173], v[164:165]
	global_store_dwordx4 v155, v[116:119], s[76:77] offset:512 nt
	global_store_dwordx4 v155, v[112:115], s[76:77] offset:528 nt
	s_add_u32 s72, s46, 0x40000
	s_addc_u32 s73, s47, 0
	s_add_u32 s74, s6, 0x40000
	s_addc_u32 s75, s7, 0
	global_load_dword v198, v156, s[70:71] offset:512 sc1
	global_load_dwordx4 v[182:185], v147, s[72:73]
	global_load_dwordx4 v[190:193], v147, s[74:75]
	global_load_dwordx4 v[186:189], v147, s[72:73] offset:256
	global_load_dwordx4 v[194:197], v147, s[74:75] offset:256
	s_waitcnt vmcnt(19)
;     __device__ __forceinline__ void operator()(const f32x4 (&acc)[2][2][4][2], const Unit& u, int wr, int wc, int fr, int fq) const {
;     ...
;             for (int m = 0; m < 4; ++m) { const int row = row0 + ai * HALF + m * 16; const size_t off = (size_t)row * ldc + col0;
;                 const float nrl = -1.4426950408889634f * __builtin_amdgcn_rsqf(__hip_atomic_load(rowsq + row, __ATOMIC_RELAXED, __HIP_MEMORY_SCOPE_AGENT) * (1.f / (float)ldc) + eps);
; #pragma unroll
;                 for (int bj = 0; bj < 2; ++bj) { const size_t o2 = off + bj * HALF; const u32x4 xw = *(const u32x4*)(xb + o2), g = *(const u32x4*)(pl + o2);
;                     f32x4 b0, b1, p0, p1;
;                     b0[0] = __uint_as_float(xw.x << 16); b0[1] = __uint_as_float(xw.x & 0xffff0000u); b0[2] = __uint_as_float(xw.y << 16); b0[3] = __uint_as_float(xw.y & 0xffff0000u);
;                     b1[0] = __uint_as_float(xw.z << 16); b1[1] = __uint_as_float(xw.z & 0xffff0000u); b1[2] = __uint_as_float(xw.w << 16); b1[3] = __uint_as_float(xw.w & 0xffff0000u);
;                     p0[0] = __uint_as_float(g.x << 16); p0[1] = __uint_as_float(g.x & 0xffff0000u); p0[2] = __uint_as_float(g.y << 16); p0[3] = __uint_as_float(g.y & 0xffff0000u);
;                     p1[0] = __uint_as_float(g.z << 16); p1[1] = __uint_as_float(g.z & 0xffff0000u); p1[2] = __uint_as_float(g.w << 16); p1[3] = __uint_as_float(g.w & 0xffff0000u);
;                     f32x4 s0, s1;
; #pragma unroll
;                     for (int e = 0; e < 4; ++e) { s0[e] = __builtin_amdgcn_rcpf(1.f + __builtin_amdgcn_exp2f(nrl * acc[ai][bj][m][0][e])); s1[e] = __builtin_amdgcn_rcpf(1.f + __builtin_amdgcn_exp2f(nrl * acc[ai][bj][m][1][e])); }
;                     *(f32x4*)(out + o2) = b0 + s0 * p0; *(f32x4*)(out + o2 + 4) = b1 + s1 * p1; }
	v_fmamk_f32 v157, v216, 0x3a800000, v154
	v_rsq_f32_e32 v157, v157
	s_add_u32 s76, s80, 0x10000
	s_addc_u32 s77, s81, 0
	v_mul_f32_e32 v157, 0xbfb8aa3b, v157
	v_mul_f32_e32 v104, v104, v157
	v_mul_f32_e32 v105, v105, v157
	v_mul_f32_e32 v106, v106, v157
	v_mul_f32_e32 v107, v107, v157
	v_mul_f32_e32 v108, v108, v157
	v_mul_f32_e32 v109, v109, v157
	v_mul_f32_e32 v110, v110, v157
	v_mul_f32_e32 v111, v111, v157
	v_exp_f32_e32 v104, v104
	v_exp_f32_e32 v105, v105
	v_exp_f32_e32 v106, v106
	v_exp_f32_e32 v107, v107
	v_exp_f32_e32 v108, v108
	v_exp_f32_e32 v109, v109
	v_exp_f32_e32 v110, v110
	v_exp_f32_e32 v111, v111
	v_add_f32_e32 v104, 1.0, v104
	v_add_f32_e32 v105, 1.0, v105
	v_add_f32_e32 v106, 1.0, v106
	v_add_f32_e32 v107, 1.0, v107
	v_add_f32_e32 v108, 1.0, v108
	v_add_f32_e32 v109, 1.0, v109
	v_add_f32_e32 v110, 1.0, v110
	v_add_f32_e32 v111, 1.0, v111
	v_rcp_f32_e32 v104, v104
	v_rcp_f32_e32 v105, v105
	v_rcp_f32_e32 v106, v106
	v_rcp_f32_e32 v107, v107
	v_rcp_f32_e32 v108, v108
	v_rcp_f32_e32 v109, v109
	v_rcp_f32_e32 v110, v110
	v_rcp_f32_e32 v111, v111
	v_lshlrev_b32_e32 v158, 16, v200
	v_and_b32_e32 v159, 0xffff0000, v200
	v_lshlrev_b32_e32 v166, 16, v208
	v_and_b32_e32 v167, 0xffff0000, v208
	v_lshlrev_b32_e32 v160, 16, v201
	v_and_b32_e32 v161, 0xffff0000, v201
	v_lshlrev_b32_e32 v168, 16, v209
	v_and_b32_e32 v169, 0xffff0000, v209
	v_lshlrev_b32_e32 v162, 16, v202
	v_and_b32_e32 v163, 0xffff0000, v202
	v_lshlrev_b32_e32 v170, 16, v210
	v_and_b32_e32 v171, 0xffff0000, v210
	v_lshlrev_b32_e32 v164, 16, v203
	v_and_b32_e32 v165, 0xffff0000, v203
	v_lshlrev_b32_e32 v172, 16, v211
	v_and_b32_e32 v173, 0xffff0000, v211
	v_pk_fma_f32 v[108:109], v[108:109], v[166:167], v[158:159]
	v_pk_fma_f32 v[110:111], v[110:111], v[168:169], v[160:161]
	v_pk_fma_f32 v[104:105], v[104:105], v[170:171], v[162:163]
	v_pk_fma_f32 v[106:107], v[106:107], v[172:173], v[164:165]
	global_store_dwordx4 v155, v[108:111], s[76:77] nt
	global_store_dwordx4 v155, v[104:107], s[76:77] offset:16 nt
	v_mul_f32_e32 v96, v96, v157
	v_mul_f32_e32 v97, v97, v157
	v_mul_f32_e32 v98, v98, v157
	v_mul_f32_e32 v99, v99, v157
	v_mul_f32_e32 v100, v100, v157
	v_mul_f32_e32 v101, v101, v157
	v_mul_f32_e32 v102, v102, v157
	v_mul_f32_e32 v103, v103, v157
	v_exp_f32_e32 v96, v96
	v_exp_f32_e32 v97, v97
	v_exp_f32_e32 v98, v98
	v_exp_f32_e32 v99, v99
	v_exp_f32_e32 v100, v100
	v_exp_f32_e32 v101, v101
	v_exp_f32_e32 v102, v102
	v_exp_f32_e32 v103, v103
	v_add_f32_e32 v96, 1.0, v96
	v_add_f32_e32 v97, 1.0, v97
	v_add_f32_e32 v98, 1.0, v98
	v_add_f32_e32 v99, 1.0, v99
	v_add_f32_e32 v100, 1.0, v100
	v_add_f32_e32 v101, 1.0, v101
	v_add_f32_e32 v102, 1.0, v102
	v_add_f32_e32 v103, 1.0, v103
	v_rcp_f32_e32 v96, v96
	v_rcp_f32_e32 v97, v97
	v_rcp_f32_e32 v98, v98
	v_rcp_f32_e32 v99, v99
	v_rcp_f32_e32 v100, v100
	v_rcp_f32_e32 v101, v101
	v_rcp_f32_e32 v102, v102
	v_rcp_f32_e32 v103, v103
	v_lshlrev_b32_e32 v158, 16, v204
	v_and_b32_e32 v159, 0xffff0000, v204
	v_lshlrev_b32_e32 v166, 16, v212
	v_and_b32_e32 v167, 0xffff0000, v212
	v_lshlrev_b32_e32 v160, 16, v205
	v_and_b32_e32 v161, 0xffff0000, v205
	v_lshlrev_b32_e32 v168, 16, v213
	v_and_b32_e32 v169, 0xffff0000, v213
	v_lshlrev_b32_e32 v162, 16, v206
	v_and_b32_e32 v163, 0xffff0000, v206
	v_lshlrev_b32_e32 v170, 16, v214
	v_and_b32_e32 v171, 0xffff0000, v214
	v_lshlrev_b32_e32 v164, 16, v207
	v_and_b32_e32 v165, 0xffff0000, v207
	v_lshlrev_b32_e32 v172, 16, v215
	v_and_b32_e32 v173, 0xffff0000, v215
	v_pk_fma_f32 v[100:101], v[100:101], v[166:167], v[158:159]
	v_pk_fma_f32 v[102:103], v[102:103], v[168:169], v[160:161]
	v_pk_fma_f32 v[96:97], v[96:97], v[170:171], v[162:163]
	v_pk_fma_f32 v[98:99], v[98:99], v[172:173], v[164:165]
	global_store_dwordx4 v155, v[100:103], s[76:77] offset:512 nt
	global_store_dwordx4 v155, v[96:99], s[76:77] offset:528 nt
	s_add_u32 s72, s46, 0x48000
	s_addc_u32 s73, s47, 0
	s_add_u32 s74, s6, 0x48000
	s_addc_u32 s75, s7, 0
	global_load_dword v216, v156, s[70:71] offset:576 sc1
	global_load_dwordx4 v[200:203], v147, s[72:73]
	global_load_dwordx4 v[208:211], v147, s[74:75]
	global_load_dwordx4 v[204:207], v147, s[72:73] offset:256
	global_load_dwordx4 v[212:215], v147, s[74:75] offset:256
	s_waitcnt vmcnt(23)
;     __device__ __forceinline__ void operator()(const f32x4 (&acc)[2][2][4][2], const Unit& u, int wr, int wc, int fr, int fq) const {
;     ...
;             for (int m = 0; m < 4; ++m) { const int row = row0 + ai * HALF + m * 16; const size_t off = (size_t)row * ldc + col0;
;                 const float nrl = -1.4426950408889634f * __builtin_amdgcn_rsqf(__hip_atomic_load(rowsq + row, __ATOMIC_RELAXED, __HIP_MEMORY_SCOPE_AGENT) * (1.f / (float)ldc) + eps);
; #pragma unroll
;                 for (int bj = 0; bj < 2; ++bj) { const size_t o2 = off + bj * HALF; const u32x4 xw = *(const u32x4*)(xb + o2), g = *(const u32x4*)(pl + o2);
;                     f32x4 b0, b1, p0, p1;
;                     b0[0] = __uint_as_float(xw.x << 16); b0[1] = __uint_as_float(xw.x & 0xffff0000u); b0[2] = __uint_as_float(xw.y << 16); b0[3] = __uint_as_float(xw.y & 0xffff0000u);
;                     b1[0] = __uint_as_float(xw.z << 16); b1[1] = __uint_as_float(xw.z & 0xffff0000u); b1[2] = __uint_as_float(xw.w << 16); b1[3] = __uint_as_float(xw.w & 0xffff0000u);
;                     p0[0] = __uint_as_float(g.x << 16); p0[1] = __uint_as_float(g.x & 0xffff0000u); p0[2] = __uint_as_float(g.y << 16); p0[3] = __uint_as_float(g.y & 0xffff0000u);
;                     p1[0] = __uint_as_float(g.z << 16); p1[1] = __uint_as_float(g.z & 0xffff0000u); p1[2] = __uint_as_float(g.w << 16); p1[3] = __uint_as_float(g.w & 0xffff0000u);
;                     f32x4 s0, s1;
; #pragma unroll
;                     for (int e = 0; e < 4; ++e) { s0[e] = __builtin_amdgcn_rcpf(1.f + __builtin_amdgcn_exp2f(nrl * acc[ai][bj][m][0][e])); s1[e] = __builtin_amdgcn_rcpf(1.f + __builtin_amdgcn_exp2f(nrl * acc[ai][bj][m][1][e])); }
;                     *(f32x4*)(out + o2) = b0 + s0 * p0; *(f32x4*)(out + o2 + 4) = b1 + s1 * p1; }
	v_fmamk_f32 v157, v234, 0x3a800000, v154
	v_rsq_f32_e32 v157, v157
	s_add_u32 s76, s80, 0x20000
	s_addc_u32 s77, s81, 0
	v_mul_f32_e32 v157, 0xbfb8aa3b, v157
	v_mul_f32_e32 v88, v88, v157
	v_mul_f32_e32 v89, v89, v157
	v_mul_f32_e32 v90, v90, v157
	v_mul_f32_e32 v91, v91, v157
	v_mul_f32_e32 v92, v92, v157
	v_mul_f32_e32 v93, v93, v157
	v_mul_f32_e32 v94, v94, v157
	v_mul_f32_e32 v95, v95, v157
	v_exp_f32_e32 v88, v88
	v_exp_f32_e32 v89, v89
	v_exp_f32_e32 v90, v90
	v_exp_f32_e32 v91, v91
	v_exp_f32_e32 v92, v92
	v_exp_f32_e32 v93, v93
	v_exp_f32_e32 v94, v94
	v_exp_f32_e32 v95, v95
	v_add_f32_e32 v88, 1.0, v88
	v_add_f32_e32 v89, 1.0, v89
	v_add_f32_e32 v90, 1.0, v90
	v_add_f32_e32 v91, 1.0, v91
	v_add_f32_e32 v92, 1.0, v92
	v_add_f32_e32 v93, 1.0, v93
	v_add_f32_e32 v94, 1.0, v94
	v_add_f32_e32 v95, 1.0, v95
	v_rcp_f32_e32 v88, v88
	v_rcp_f32_e32 v89, v89
	v_rcp_f32_e32 v90, v90
	v_rcp_f32_e32 v91, v91
	v_rcp_f32_e32 v92, v92
	v_rcp_f32_e32 v93, v93
	v_rcp_f32_e32 v94, v94
	v_rcp_f32_e32 v95, v95
	v_lshlrev_b32_e32 v158, 16, v218
	v_and_b32_e32 v159, 0xffff0000, v218
	v_lshlrev_b32_e32 v166, 16, v226
	v_and_b32_e32 v167, 0xffff0000, v226
	v_lshlrev_b32_e32 v160, 16, v219
	v_and_b32_e32 v161, 0xffff0000, v219
	v_lshlrev_b32_e32 v168, 16, v227
	v_and_b32_e32 v169, 0xffff0000, v227
	v_lshlrev_b32_e32 v162, 16, v220
	v_and_b32_e32 v163, 0xffff0000, v220
	v_lshlrev_b32_e32 v170, 16, v228
	v_and_b32_e32 v171, 0xffff0000, v228
	v_lshlrev_b32_e32 v164, 16, v221
	v_and_b32_e32 v165, 0xffff0000, v221
	v_lshlrev_b32_e32 v172, 16, v229
	v_and_b32_e32 v173, 0xffff0000, v229
	v_pk_fma_f32 v[92:93], v[92:93], v[166:167], v[158:159]
	v_pk_fma_f32 v[94:95], v[94:95], v[168:169], v[160:161]
	v_pk_fma_f32 v[88:89], v[88:89], v[170:171], v[162:163]
	v_pk_fma_f32 v[90:91], v[90:91], v[172:173], v[164:165]
	global_store_dwordx4 v155, v[92:95], s[76:77] nt
	global_store_dwordx4 v155, v[88:91], s[76:77] offset:16 nt
	v_mul_f32_e32 v80, v80, v157
	v_mul_f32_e32 v81, v81, v157
	v_mul_f32_e32 v82, v82, v157
	v_mul_f32_e32 v83, v83, v157
	v_mul_f32_e32 v84, v84, v157
	v_mul_f32_e32 v85, v85, v157
	v_mul_f32_e32 v86, v86, v157
	v_mul_f32_e32 v87, v87, v157
	v_exp_f32_e32 v80, v80
	v_exp_f32_e32 v81, v81
	v_exp_f32_e32 v82, v82
	v_exp_f32_e32 v83, v83
	v_exp_f32_e32 v84, v84
	v_exp_f32_e32 v85, v85
	v_exp_f32_e32 v86, v86
	v_exp_f32_e32 v87, v87
	v_add_f32_e32 v80, 1.0, v80
	v_add_f32_e32 v81, 1.0, v81
	v_add_f32_e32 v82, 1.0, v82
	v_add_f32_e32 v83, 1.0, v83
	v_add_f32_e32 v84, 1.0, v84
	v_add_f32_e32 v85, 1.0, v85
	v_add_f32_e32 v86, 1.0, v86
	v_add_f32_e32 v87, 1.0, v87
	v_rcp_f32_e32 v80, v80
	v_rcp_f32_e32 v81, v81
	v_rcp_f32_e32 v82, v82
	v_rcp_f32_e32 v83, v83
	v_rcp_f32_e32 v84, v84
	v_rcp_f32_e32 v85, v85
	v_rcp_f32_e32 v86, v86
	v_rcp_f32_e32 v87, v87
	v_lshlrev_b32_e32 v158, 16, v222
	v_and_b32_e32 v159, 0xffff0000, v222
	v_lshlrev_b32_e32 v166, 16, v230
	v_and_b32_e32 v167, 0xffff0000, v230
	v_lshlrev_b32_e32 v160, 16, v223
	v_and_b32_e32 v161, 0xffff0000, v223
	v_lshlrev_b32_e32 v168, 16, v231
	v_and_b32_e32 v169, 0xffff0000, v231
	v_lshlrev_b32_e32 v162, 16, v224
	v_and_b32_e32 v163, 0xffff0000, v224
	v_lshlrev_b32_e32 v170, 16, v232
	v_and_b32_e32 v171, 0xffff0000, v232
	v_lshlrev_b32_e32 v164, 16, v225
	v_and_b32_e32 v165, 0xffff0000, v225
	v_lshlrev_b32_e32 v172, 16, v233
	v_and_b32_e32 v173, 0xffff0000, v233
	v_pk_fma_f32 v[84:85], v[84:85], v[166:167], v[158:159]
	v_pk_fma_f32 v[86:87], v[86:87], v[168:169], v[160:161]
	v_pk_fma_f32 v[80:81], v[80:81], v[170:171], v[162:163]
	v_pk_fma_f32 v[82:83], v[82:83], v[172:173], v[164:165]
	global_store_dwordx4 v155, v[84:87], s[76:77] offset:512 nt
	global_store_dwordx4 v155, v[80:83], s[76:77] offset:528 nt
	s_add_u32 s72, s46, 0x50000
	s_addc_u32 s73, s47, 0
	s_add_u32 s74, s6, 0x50000
	s_addc_u32 s75, s7, 0
	global_load_dword v234, v156, s[70:71] offset:640 sc1
	global_load_dwordx4 v[218:221], v147, s[72:73]
	global_load_dwordx4 v[226:229], v147, s[74:75]
	global_load_dwordx4 v[222:225], v147, s[72:73] offset:256
	global_load_dwordx4 v[230:233], v147, s[74:75] offset:256
	s_waitcnt vmcnt(27)
	v_fmamk_f32 v157, v252, 0x3a800000, v154
	v_rsq_f32_e32 v157, v157
	s_add_u32 s76, s80, 0x30000
	s_addc_u32 s77, s81, 0
	v_mul_f32_e32 v157, 0xbfb8aa3b, v157
	v_mul_f32_e32 v72, v72, v157
	v_mul_f32_e32 v73, v73, v157
	v_mul_f32_e32 v74, v74, v157
	v_mul_f32_e32 v75, v75, v157
	v_mul_f32_e32 v76, v76, v157
	v_mul_f32_e32 v77, v77, v157
	v_mul_f32_e32 v78, v78, v157
	v_mul_f32_e32 v79, v79, v157
	v_exp_f32_e32 v72, v72
	v_exp_f32_e32 v73, v73
	v_exp_f32_e32 v74, v74
	v_exp_f32_e32 v75, v75
	v_exp_f32_e32 v76, v76
	v_exp_f32_e32 v77, v77
	v_exp_f32_e32 v78, v78
	v_exp_f32_e32 v79, v79
	v_add_f32_e32 v72, 1.0, v72
	v_add_f32_e32 v73, 1.0, v73
	v_add_f32_e32 v74, 1.0, v74
	v_add_f32_e32 v75, 1.0, v75
	v_add_f32_e32 v76, 1.0, v76
	v_add_f32_e32 v77, 1.0, v77
	v_add_f32_e32 v78, 1.0, v78
	v_add_f32_e32 v79, 1.0, v79
	v_rcp_f32_e32 v72, v72
	v_rcp_f32_e32 v73, v73
	v_rcp_f32_e32 v74, v74
	v_rcp_f32_e32 v75, v75
	v_rcp_f32_e32 v76, v76
	v_rcp_f32_e32 v77, v77
	v_rcp_f32_e32 v78, v78
	v_rcp_f32_e32 v79, v79
	v_lshlrev_b32_e32 v158, 16, v236
	v_and_b32_e32 v159, 0xffff0000, v236
	v_lshlrev_b32_e32 v166, 16, v244
	v_and_b32_e32 v167, 0xffff0000, v244
	v_lshlrev_b32_e32 v160, 16, v237
	v_and_b32_e32 v161, 0xffff0000, v237
	v_lshlrev_b32_e32 v168, 16, v245
	v_and_b32_e32 v169, 0xffff0000, v245
	v_lshlrev_b32_e32 v162, 16, v238
	v_and_b32_e32 v163, 0xffff0000, v238
	v_lshlrev_b32_e32 v170, 16, v246
	v_and_b32_e32 v171, 0xffff0000, v246
	v_lshlrev_b32_e32 v164, 16, v239
	v_and_b32_e32 v165, 0xffff0000, v239
;     __device__ __forceinline__ void operator()(const f32x4 (&acc)[2][2][4][2], const Unit& u, int wr, int wc, int fr, int fq) const {
;     ...
;             for (int m = 0; m < 4; ++m) { const int row = row0 + ai * HALF + m * 16; const size_t off = (size_t)row * ldc + col0;
;                 const float nrl = -1.4426950408889634f * __builtin_amdgcn_rsqf(__hip_atomic_load(rowsq + row, __ATOMIC_RELAXED, __HIP_MEMORY_SCOPE_AGENT) * (1.f / (float)ldc) + eps);
; #pragma unroll
;                 for (int bj = 0; bj < 2; ++bj) { const size_t o2 = off + bj * HALF; const u32x4 xw = *(const u32x4*)(xb + o2), g = *(const u32x4*)(pl + o2);
;                     f32x4 b0, b1, p0, p1;
;                     b0[0] = __uint_as_float(xw.x << 16); b0[1] = __uint_as_float(xw.x & 0xffff0000u); b0[2] = __uint_as_float(xw.y << 16); b0[3] = __uint_as_float(xw.y & 0xffff0000u);
;                     b1[0] = __uint_as_float(xw.z << 16); b1[1] = __uint_as_float(xw.z & 0xffff0000u); b1[2] = __uint_as_float(xw.w << 16); b1[3] = __uint_as_float(xw.w & 0xffff0000u);
;                     p0[0] = __uint_as_float(g.x << 16); p0[1] = __uint_as_float(g.x & 0xffff0000u); p0[2] = __uint_as_float(g.y << 16); p0[3] = __uint_as_float(g.y & 0xffff0000u);
;                     p1[0] = __uint_as_float(g.z << 16); p1[1] = __uint_as_float(g.z & 0xffff0000u); p1[2] = __uint_as_float(g.w << 16); p1[3] = __uint_as_float(g.w & 0xffff0000u);
;                     f32x4 s0, s1;
; #pragma unroll
;                     for (int e = 0; e < 4; ++e) { s0[e] = __builtin_amdgcn_rcpf(1.f + __builtin_amdgcn_exp2f(nrl * acc[ai][bj][m][0][e])); s1[e] = __builtin_amdgcn_rcpf(1.f + __builtin_amdgcn_exp2f(nrl * acc[ai][bj][m][1][e])); }
;                     *(f32x4*)(out + o2) = b0 + s0 * p0; *(f32x4*)(out + o2 + 4) = b1 + s1 * p1; }
	v_lshlrev_b32_e32 v172, 16, v247
	v_and_b32_e32 v173, 0xffff0000, v247
	v_pk_fma_f32 v[76:77], v[76:77], v[166:167], v[158:159]
	v_pk_fma_f32 v[78:79], v[78:79], v[168:169], v[160:161]
	v_pk_fma_f32 v[72:73], v[72:73], v[170:171], v[162:163]
	v_pk_fma_f32 v[74:75], v[74:75], v[172:173], v[164:165]
	global_store_dwordx4 v155, v[76:79], s[76:77] nt
	global_store_dwordx4 v155, v[72:75], s[76:77] offset:16 nt
	v_mul_f32_e32 v64, v64, v157
	v_mul_f32_e32 v65, v65, v157
	v_mul_f32_e32 v66, v66, v157
	v_mul_f32_e32 v67, v67, v157
	v_mul_f32_e32 v68, v68, v157
	v_mul_f32_e32 v69, v69, v157
	v_mul_f32_e32 v70, v70, v157
	v_mul_f32_e32 v71, v71, v157
	v_exp_f32_e32 v64, v64
	v_exp_f32_e32 v65, v65
	v_exp_f32_e32 v66, v66
	v_exp_f32_e32 v67, v67
	v_exp_f32_e32 v68, v68
	v_exp_f32_e32 v69, v69
	v_exp_f32_e32 v70, v70
	v_exp_f32_e32 v71, v71
	v_add_f32_e32 v64, 1.0, v64
	v_add_f32_e32 v65, 1.0, v65
	v_add_f32_e32 v66, 1.0, v66
	v_add_f32_e32 v67, 1.0, v67
	v_add_f32_e32 v68, 1.0, v68
	v_add_f32_e32 v69, 1.0, v69
	v_add_f32_e32 v70, 1.0, v70
	v_add_f32_e32 v71, 1.0, v71
	v_rcp_f32_e32 v64, v64
	v_rcp_f32_e32 v65, v65
	v_rcp_f32_e32 v66, v66
	v_rcp_f32_e32 v67, v67
	v_rcp_f32_e32 v68, v68
	v_rcp_f32_e32 v69, v69
	v_rcp_f32_e32 v70, v70
	v_rcp_f32_e32 v71, v71
	v_lshlrev_b32_e32 v158, 16, v240
	v_and_b32_e32 v159, 0xffff0000, v240
	v_lshlrev_b32_e32 v166, 16, v248
	v_and_b32_e32 v167, 0xffff0000, v248
	v_lshlrev_b32_e32 v160, 16, v241
	v_and_b32_e32 v161, 0xffff0000, v241
	v_lshlrev_b32_e32 v168, 16, v249
	v_and_b32_e32 v169, 0xffff0000, v249
	v_lshlrev_b32_e32 v162, 16, v242
	v_and_b32_e32 v163, 0xffff0000, v242
	v_lshlrev_b32_e32 v170, 16, v250
	v_and_b32_e32 v171, 0xffff0000, v250
	v_lshlrev_b32_e32 v164, 16, v243
	v_and_b32_e32 v165, 0xffff0000, v243
	v_lshlrev_b32_e32 v172, 16, v251
	v_and_b32_e32 v173, 0xffff0000, v251
	v_pk_fma_f32 v[68:69], v[68:69], v[166:167], v[158:159]
	v_pk_fma_f32 v[70:71], v[70:71], v[168:169], v[160:161]
	v_pk_fma_f32 v[64:65], v[64:65], v[170:171], v[162:163]
	v_pk_fma_f32 v[66:67], v[66:67], v[172:173], v[164:165]
	global_store_dwordx4 v155, v[68:71], s[76:77] offset:512 nt
	global_store_dwordx4 v155, v[64:67], s[76:77] offset:528 nt
	s_add_u32 s72, s46, 0x58000
	s_addc_u32 s73, s47, 0
	s_add_u32 s74, s6, 0x58000
	s_addc_u32 s75, s7, 0
	global_load_dword v252, v156, s[70:71] offset:704 sc1
	global_load_dwordx4 v[236:239], v147, s[72:73]
	global_load_dwordx4 v[244:247], v147, s[74:75]
	global_load_dwordx4 v[240:243], v147, s[72:73] offset:256
	global_load_dwordx4 v[248:251], v147, s[74:75] offset:256
	s_waitcnt vmcnt(27)
	v_fmamk_f32 v157, v198, 0x3a800000, v154
	v_rsq_f32_e32 v157, v157
	s_add_u32 s76, s80, 0x80000
	s_addc_u32 s77, s81, 0
	v_mul_f32_e32 v157, 0xbfb8aa3b, v157
	v_mul_f32_e32 v56, v56, v157
	v_mul_f32_e32 v57, v57, v157
	v_mul_f32_e32 v58, v58, v157
	v_mul_f32_e32 v59, v59, v157
	v_mul_f32_e32 v60, v60, v157
	v_mul_f32_e32 v61, v61, v157
	v_mul_f32_e32 v62, v62, v157
	v_mul_f32_e32 v63, v63, v157
	v_exp_f32_e32 v56, v56
	v_exp_f32_e32 v57, v57
	v_exp_f32_e32 v58, v58
	v_exp_f32_e32 v59, v59
	v_exp_f32_e32 v60, v60
	v_exp_f32_e32 v61, v61
	v_exp_f32_e32 v62, v62
	v_exp_f32_e32 v63, v63
	v_add_f32_e32 v56, 1.0, v56
	v_add_f32_e32 v57, 1.0, v57
	v_add_f32_e32 v58, 1.0, v58
	v_add_f32_e32 v59, 1.0, v59
	v_add_f32_e32 v60, 1.0, v60
	v_add_f32_e32 v61, 1.0, v61
	v_add_f32_e32 v62, 1.0, v62
	v_add_f32_e32 v63, 1.0, v63
	v_rcp_f32_e32 v56, v56
	v_rcp_f32_e32 v57, v57
	v_rcp_f32_e32 v58, v58
	v_rcp_f32_e32 v59, v59
	v_rcp_f32_e32 v60, v60
	v_rcp_f32_e32 v61, v61
	v_rcp_f32_e32 v62, v62
	v_rcp_f32_e32 v63, v63
	v_lshlrev_b32_e32 v158, 16, v182
	v_and_b32_e32 v159, 0xffff0000, v182
	v_lshlrev_b32_e32 v166, 16, v190
	v_and_b32_e32 v167, 0xffff0000, v190
	v_lshlrev_b32_e32 v160, 16, v183
	v_and_b32_e32 v161, 0xffff0000, v183
	v_lshlrev_b32_e32 v168, 16, v191
	v_and_b32_e32 v169, 0xffff0000, v191
	v_lshlrev_b32_e32 v162, 16, v184
	v_and_b32_e32 v163, 0xffff0000, v184
	v_lshlrev_b32_e32 v170, 16, v192
	v_and_b32_e32 v171, 0xffff0000, v192
	v_lshlrev_b32_e32 v164, 16, v185
	v_and_b32_e32 v165, 0xffff0000, v185
	v_lshlrev_b32_e32 v172, 16, v193
	v_and_b32_e32 v173, 0xffff0000, v193
	v_pk_fma_f32 v[60:61], v[60:61], v[166:167], v[158:159]
	v_pk_fma_f32 v[62:63], v[62:63], v[168:169], v[160:161]
	v_pk_fma_f32 v[56:57], v[56:57], v[170:171], v[162:163]
	v_pk_fma_f32 v[58:59], v[58:59], v[172:173], v[164:165]
	global_store_dwordx4 v155, v[60:63], s[76:77] nt
	global_store_dwordx4 v155, v[56:59], s[76:77] offset:16 nt
	v_mul_f32_e32 v48, v48, v157
	v_mul_f32_e32 v49, v49, v157
	v_mul_f32_e32 v50, v50, v157
	v_mul_f32_e32 v51, v51, v157
	v_mul_f32_e32 v52, v52, v157
	v_mul_f32_e32 v53, v53, v157
	v_mul_f32_e32 v54, v54, v157
	v_mul_f32_e32 v55, v55, v157
	v_exp_f32_e32 v48, v48
	v_exp_f32_e32 v49, v49
	v_exp_f32_e32 v50, v50
	v_exp_f32_e32 v51, v51
	v_exp_f32_e32 v52, v52
	v_exp_f32_e32 v53, v53
	v_exp_f32_e32 v54, v54
	v_exp_f32_e32 v55, v55
	v_add_f32_e32 v48, 1.0, v48
	v_add_f32_e32 v49, 1.0, v49
	v_add_f32_e32 v50, 1.0, v50
	v_add_f32_e32 v51, 1.0, v51
	v_add_f32_e32 v52, 1.0, v52
	v_add_f32_e32 v53, 1.0, v53
	v_add_f32_e32 v54, 1.0, v54
	v_add_f32_e32 v55, 1.0, v55
	v_rcp_f32_e32 v48, v48
	v_rcp_f32_e32 v49, v49
	v_rcp_f32_e32 v50, v50
	v_rcp_f32_e32 v51, v51
	v_rcp_f32_e32 v52, v52
	v_rcp_f32_e32 v53, v53
	v_rcp_f32_e32 v54, v54
	v_rcp_f32_e32 v55, v55
	v_lshlrev_b32_e32 v158, 16, v186
	v_and_b32_e32 v159, 0xffff0000, v186
	v_lshlrev_b32_e32 v166, 16, v194
	v_and_b32_e32 v167, 0xffff0000, v194
	v_lshlrev_b32_e32 v160, 16, v187
	v_and_b32_e32 v161, 0xffff0000, v187
	v_lshlrev_b32_e32 v168, 16, v195
	v_and_b32_e32 v169, 0xffff0000, v195
	v_lshlrev_b32_e32 v162, 16, v188
	v_and_b32_e32 v163, 0xffff0000, v188
	v_lshlrev_b32_e32 v170, 16, v196
	v_and_b32_e32 v171, 0xffff0000, v196
	v_lshlrev_b32_e32 v164, 16, v189
	v_and_b32_e32 v165, 0xffff0000, v189
	v_lshlrev_b32_e32 v172, 16, v197
	v_and_b32_e32 v173, 0xffff0000, v197
	v_pk_fma_f32 v[52:53], v[52:53], v[166:167], v[158:159]
	v_pk_fma_f32 v[54:55], v[54:55], v[168:169], v[160:161]
	v_pk_fma_f32 v[48:49], v[48:49], v[170:171], v[162:163]
	v_pk_fma_f32 v[50:51], v[50:51], v[172:173], v[164:165]
	global_store_dwordx4 v155, v[52:55], s[76:77] offset:512 nt
	global_store_dwordx4 v155, v[48:51], s[76:77] offset:528 nt
	s_waitcnt vmcnt(22)
;     __device__ __forceinline__ void operator()(const f32x4 (&acc)[2][2][4][2], const Unit& u, int wr, int wc, int fr, int fq) const {
;     ...
;             for (int m = 0; m < 4; ++m) { const int row = row0 + ai * HALF + m * 16; const size_t off = (size_t)row * ldc + col0;
;                 const float nrl = -1.4426950408889634f * __builtin_amdgcn_rsqf(__hip_atomic_load(rowsq + row, __ATOMIC_RELAXED, __HIP_MEMORY_SCOPE_AGENT) * (1.f / (float)ldc) + eps);
; #pragma unroll
;                 for (int bj = 0; bj < 2; ++bj) { const size_t o2 = off + bj * HALF; const u32x4 xw = *(const u32x4*)(xb + o2), g = *(const u32x4*)(pl + o2);
;                     f32x4 b0, b1, p0, p1;
;                     b0[0] = __uint_as_float(xw.x << 16); b0[1] = __uint_as_float(xw.x & 0xffff0000u); b0[2] = __uint_as_float(xw.y << 16); b0[3] = __uint_as_float(xw.y & 0xffff0000u);
;                     b1[0] = __uint_as_float(xw.z << 16); b1[1] = __uint_as_float(xw.z & 0xffff0000u); b1[2] = __uint_as_float(xw.w << 16); b1[3] = __uint_as_float(xw.w & 0xffff0000u);
;                     p0[0] = __uint_as_float(g.x << 16); p0[1] = __uint_as_float(g.x & 0xffff0000u); p0[2] = __uint_as_float(g.y << 16); p0[3] = __uint_as_float(g.y & 0xffff0000u);
;                     p1[0] = __uint_as_float(g.z << 16); p1[1] = __uint_as_float(g.z & 0xffff0000u); p1[2] = __uint_as_float(g.w << 16); p1[3] = __uint_as_float(g.w & 0xffff0000u);
;                     f32x4 s0, s1;
; #pragma unroll
;                     for (int e = 0; e < 4; ++e) { s0[e] = __builtin_amdgcn_rcpf(1.f + __builtin_amdgcn_exp2f(nrl * acc[ai][bj][m][0][e])); s1[e] = __builtin_amdgcn_rcpf(1.f + __builtin_amdgcn_exp2f(nrl * acc[ai][bj][m][1][e])); }
;                     *(f32x4*)(out + o2) = b0 + s0 * p0; *(f32x4*)(out + o2 + 4) = b1 + s1 * p1; }
	v_fmamk_f32 v157, v216, 0x3a800000, v154
	v_rsq_f32_e32 v157, v157
	s_add_u32 s76, s80, 0x90000
	s_addc_u32 s77, s81, 0
	v_mul_f32_e32 v157, 0xbfb8aa3b, v157
	v_mul_f32_e32 v40, v40, v157
	v_mul_f32_e32 v41, v41, v157
	v_mul_f32_e32 v42, v42, v157
	v_mul_f32_e32 v43, v43, v157
	v_mul_f32_e32 v44, v44, v157
	v_mul_f32_e32 v45, v45, v157
	v_mul_f32_e32 v46, v46, v157
	v_mul_f32_e32 v47, v47, v157
	v_exp_f32_e32 v40, v40
	v_exp_f32_e32 v41, v41
	v_exp_f32_e32 v42, v42
	v_exp_f32_e32 v43, v43
	v_exp_f32_e32 v44, v44
	v_exp_f32_e32 v45, v45
	v_exp_f32_e32 v46, v46
	v_exp_f32_e32 v47, v47
	v_add_f32_e32 v40, 1.0, v40
	v_add_f32_e32 v41, 1.0, v41
	v_add_f32_e32 v42, 1.0, v42
	v_add_f32_e32 v43, 1.0, v43
	v_add_f32_e32 v44, 1.0, v44
	v_add_f32_e32 v45, 1.0, v45
	v_add_f32_e32 v46, 1.0, v46
	v_add_f32_e32 v47, 1.0, v47
	v_rcp_f32_e32 v40, v40
	v_rcp_f32_e32 v41, v41
	v_rcp_f32_e32 v42, v42
	v_rcp_f32_e32 v43, v43
	v_rcp_f32_e32 v44, v44
	v_rcp_f32_e32 v45, v45
	v_rcp_f32_e32 v46, v46
	v_rcp_f32_e32 v47, v47
	v_lshlrev_b32_e32 v158, 16, v200
	v_and_b32_e32 v159, 0xffff0000, v200
	v_lshlrev_b32_e32 v166, 16, v208
	v_and_b32_e32 v167, 0xffff0000, v208
	v_lshlrev_b32_e32 v160, 16, v201
	v_and_b32_e32 v161, 0xffff0000, v201
	v_lshlrev_b32_e32 v168, 16, v209
	v_and_b32_e32 v169, 0xffff0000, v209
	v_lshlrev_b32_e32 v162, 16, v202
	v_and_b32_e32 v163, 0xffff0000, v202
	v_lshlrev_b32_e32 v170, 16, v210
	v_and_b32_e32 v171, 0xffff0000, v210
	v_lshlrev_b32_e32 v164, 16, v203
	v_and_b32_e32 v165, 0xffff0000, v203
	v_lshlrev_b32_e32 v172, 16, v211
	v_and_b32_e32 v173, 0xffff0000, v211
	v_pk_fma_f32 v[44:45], v[44:45], v[166:167], v[158:159]
	v_pk_fma_f32 v[46:47], v[46:47], v[168:169], v[160:161]
	v_pk_fma_f32 v[40:41], v[40:41], v[170:171], v[162:163]
	v_pk_fma_f32 v[42:43], v[42:43], v[172:173], v[164:165]
	global_store_dwordx4 v155, v[44:47], s[76:77] nt
	global_store_dwordx4 v155, v[40:43], s[76:77] offset:16 nt
	v_mul_f32_e32 v32, v32, v157
	v_mul_f32_e32 v33, v33, v157
	v_mul_f32_e32 v34, v34, v157
	v_mul_f32_e32 v35, v35, v157
	v_mul_f32_e32 v36, v36, v157
	v_mul_f32_e32 v37, v37, v157
	v_mul_f32_e32 v38, v38, v157
	v_mul_f32_e32 v39, v39, v157
	v_exp_f32_e32 v32, v32
	v_exp_f32_e32 v33, v33
	v_exp_f32_e32 v34, v34
	v_exp_f32_e32 v35, v35
	v_exp_f32_e32 v36, v36
	v_exp_f32_e32 v37, v37
	v_exp_f32_e32 v38, v38
	v_exp_f32_e32 v39, v39
	v_add_f32_e32 v32, 1.0, v32
	v_add_f32_e32 v33, 1.0, v33
	v_add_f32_e32 v34, 1.0, v34
	v_add_f32_e32 v35, 1.0, v35
	v_add_f32_e32 v36, 1.0, v36
	v_add_f32_e32 v37, 1.0, v37
	v_add_f32_e32 v38, 1.0, v38
	v_add_f32_e32 v39, 1.0, v39
	v_rcp_f32_e32 v32, v32
	v_rcp_f32_e32 v33, v33
	v_rcp_f32_e32 v34, v34
	v_rcp_f32_e32 v35, v35
	v_rcp_f32_e32 v36, v36
	v_rcp_f32_e32 v37, v37
	v_rcp_f32_e32 v38, v38
	v_rcp_f32_e32 v39, v39
	v_lshlrev_b32_e32 v158, 16, v204
	v_and_b32_e32 v159, 0xffff0000, v204
	v_lshlrev_b32_e32 v166, 16, v212
	v_and_b32_e32 v167, 0xffff0000, v212
	v_lshlrev_b32_e32 v160, 16, v205
	v_and_b32_e32 v161, 0xffff0000, v205
	v_lshlrev_b32_e32 v168, 16, v213
	v_and_b32_e32 v169, 0xffff0000, v213
	v_lshlrev_b32_e32 v162, 16, v206
	v_and_b32_e32 v163, 0xffff0000, v206
	v_lshlrev_b32_e32 v170, 16, v214
	v_and_b32_e32 v171, 0xffff0000, v214
	v_lshlrev_b32_e32 v164, 16, v207
	v_and_b32_e32 v165, 0xffff0000, v207
	v_lshlrev_b32_e32 v172, 16, v215
	v_and_b32_e32 v173, 0xffff0000, v215
	v_pk_fma_f32 v[36:37], v[36:37], v[166:167], v[158:159]
	v_pk_fma_f32 v[38:39], v[38:39], v[168:169], v[160:161]
	v_pk_fma_f32 v[32:33], v[32:33], v[170:171], v[162:163]
	v_pk_fma_f32 v[34:35], v[34:35], v[172:173], v[164:165]
	global_store_dwordx4 v155, v[36:39], s[76:77] offset:512 nt
	global_store_dwordx4 v155, v[32:35], s[76:77] offset:528 nt
	s_waitcnt vmcnt(17)
	v_fmamk_f32 v157, v234, 0x3a800000, v154
	v_rsq_f32_e32 v157, v157
	s_add_u32 s76, s80, 0xa0000
	s_addc_u32 s77, s81, 0
	v_mul_f32_e32 v157, 0xbfb8aa3b, v157
	v_mul_f32_e32 v24, v24, v157
	v_mul_f32_e32 v25, v25, v157
	v_mul_f32_e32 v26, v26, v157
	v_mul_f32_e32 v27, v27, v157
	v_mul_f32_e32 v28, v28, v157
	v_mul_f32_e32 v29, v29, v157
	v_mul_f32_e32 v30, v30, v157
	v_mul_f32_e32 v31, v31, v157
	v_exp_f32_e32 v24, v24
	v_exp_f32_e32 v25, v25
	v_exp_f32_e32 v26, v26
	v_exp_f32_e32 v27, v27
	v_exp_f32_e32 v28, v28
	v_exp_f32_e32 v29, v29
	v_exp_f32_e32 v30, v30
	v_exp_f32_e32 v31, v31
	v_add_f32_e32 v24, 1.0, v24
	v_add_f32_e32 v25, 1.0, v25
	v_add_f32_e32 v26, 1.0, v26
	v_add_f32_e32 v27, 1.0, v27
	v_add_f32_e32 v28, 1.0, v28
	v_add_f32_e32 v29, 1.0, v29
	v_add_f32_e32 v30, 1.0, v30
	v_add_f32_e32 v31, 1.0, v31
	v_rcp_f32_e32 v24, v24
	v_rcp_f32_e32 v25, v25
	v_rcp_f32_e32 v26, v26
	v_rcp_f32_e32 v27, v27
	v_rcp_f32_e32 v28, v28
	v_rcp_f32_e32 v29, v29
	v_rcp_f32_e32 v30, v30
	v_rcp_f32_e32 v31, v31
	v_lshlrev_b32_e32 v158, 16, v218
	v_and_b32_e32 v159, 0xffff0000, v218
	v_lshlrev_b32_e32 v166, 16, v226
	v_and_b32_e32 v167, 0xffff0000, v226
	v_lshlrev_b32_e32 v160, 16, v219
	v_and_b32_e32 v161, 0xffff0000, v219
	v_lshlrev_b32_e32 v168, 16, v227
	v_and_b32_e32 v169, 0xffff0000, v227
	v_lshlrev_b32_e32 v162, 16, v220
	v_and_b32_e32 v163, 0xffff0000, v220
	v_lshlrev_b32_e32 v170, 16, v228
	v_and_b32_e32 v171, 0xffff0000, v228
	v_lshlrev_b32_e32 v164, 16, v221
	v_and_b32_e32 v165, 0xffff0000, v221
	v_lshlrev_b32_e32 v172, 16, v229
	v_and_b32_e32 v173, 0xffff0000, v229
	v_pk_fma_f32 v[28:29], v[28:29], v[166:167], v[158:159]
	v_pk_fma_f32 v[30:31], v[30:31], v[168:169], v[160:161]
	v_pk_fma_f32 v[24:25], v[24:25], v[170:171], v[162:163]
	v_pk_fma_f32 v[26:27], v[26:27], v[172:173], v[164:165]
	global_store_dwordx4 v155, v[28:31], s[76:77] nt
;     __device__ __forceinline__ void operator()(const f32x4 (&acc)[2][2][4][2], const Unit& u, int wr, int wc, int fr, int fq) const {
;     ...
;             for (int m = 0; m < 4; ++m) { const int row = row0 + ai * HALF + m * 16; const size_t off = (size_t)row * ldc + col0;
;                 const float nrl = -1.4426950408889634f * __builtin_amdgcn_rsqf(__hip_atomic_load(rowsq + row, __ATOMIC_RELAXED, __HIP_MEMORY_SCOPE_AGENT) * (1.f / (float)ldc) + eps);
; #pragma unroll
;                 for (int bj = 0; bj < 2; ++bj) { const size_t o2 = off + bj * HALF; const u32x4 xw = *(const u32x4*)(xb + o2), g = *(const u32x4*)(pl + o2);
;                     f32x4 b0, b1, p0, p1;
;                     b0[0] = __uint_as_float(xw.x << 16); b0[1] = __uint_as_float(xw.x & 0xffff0000u); b0[2] = __uint_as_float(xw.y << 16); b0[3] = __uint_as_float(xw.y & 0xffff0000u);
;                     b1[0] = __uint_as_float(xw.z << 16); b1[1] = __uint_as_float(xw.z & 0xffff0000u); b1[2] = __uint_as_float(xw.w << 16); b1[3] = __uint_as_float(xw.w & 0xffff0000u);
;                     p0[0] = __uint_as_float(g.x << 16); p0[1] = __uint_as_float(g.x & 0xffff0000u); p0[2] = __uint_as_float(g.y << 16); p0[3] = __uint_as_float(g.y & 0xffff0000u);
;                     p1[0] = __uint_as_float(g.z << 16); p1[1] = __uint_as_float(g.z & 0xffff0000u); p1[2] = __uint_as_float(g.w << 16); p1[3] = __uint_as_float(g.w & 0xffff0000u);
;                     f32x4 s0, s1;
; #pragma unroll
;                     for (int e = 0; e < 4; ++e) { s0[e] = __builtin_amdgcn_rcpf(1.f + __builtin_amdgcn_exp2f(nrl * acc[ai][bj][m][0][e])); s1[e] = __builtin_amdgcn_rcpf(1.f + __builtin_amdgcn_exp2f(nrl * acc[ai][bj][m][1][e])); }
;                     *(f32x4*)(out + o2) = b0 + s0 * p0; *(f32x4*)(out + o2 + 4) = b1 + s1 * p1; }
; template <class Epi, class Sched, bool ALIGN_EPI = false, bool SP2 = false>
; __device__ __forceinline__ void gemm_phase(PG8_LAS unsigned char* lds, const Gemm g, const Sched& S, const Epi& E) {
;     ...
;         if (!has_next) break;
; #pragma unroll
;         for (int a = 0; a < 2; ++a)
; #pragma unroll
;             for (int b = 0; b < 2; ++b)
; #pragma unroll
;                 for (int m = 0; m < 4; ++m)
; #pragma unroll
;                     for (int n = 0; n < 2; ++n) acc[a][b][m][n] = (f32x4){0.f, 0.f, 0.f, 0.f};
;         cur = nxt; cA = nA; cB = nB; ++ui;
	global_store_dwordx4 v155, v[24:27], s[76:77] offset:16 nt
	v_mul_f32_e32 v16, v16, v157
	v_mul_f32_e32 v17, v17, v157
	v_mul_f32_e32 v18, v18, v157
	v_mul_f32_e32 v19, v19, v157
	v_mul_f32_e32 v20, v20, v157
	v_mul_f32_e32 v21, v21, v157
	v_mul_f32_e32 v22, v22, v157
	v_mul_f32_e32 v23, v23, v157
	v_exp_f32_e32 v16, v16
	v_exp_f32_e32 v17, v17
	v_exp_f32_e32 v18, v18
	v_exp_f32_e32 v19, v19
	v_exp_f32_e32 v20, v20
	v_exp_f32_e32 v21, v21
	v_exp_f32_e32 v22, v22
	v_exp_f32_e32 v23, v23
	v_add_f32_e32 v16, 1.0, v16
	v_add_f32_e32 v17, 1.0, v17
	v_add_f32_e32 v18, 1.0, v18
	v_add_f32_e32 v19, 1.0, v19
	v_add_f32_e32 v20, 1.0, v20
	v_add_f32_e32 v21, 1.0, v21
	v_add_f32_e32 v22, 1.0, v22
	v_add_f32_e32 v23, 1.0, v23
	v_rcp_f32_e32 v16, v16
	v_rcp_f32_e32 v17, v17
	v_rcp_f32_e32 v18, v18
	v_rcp_f32_e32 v19, v19
	v_rcp_f32_e32 v20, v20
	v_rcp_f32_e32 v21, v21
	v_rcp_f32_e32 v22, v22
	v_rcp_f32_e32 v23, v23
	v_lshlrev_b32_e32 v158, 16, v222
	v_and_b32_e32 v159, 0xffff0000, v222
	v_lshlrev_b32_e32 v166, 16, v230
	v_and_b32_e32 v167, 0xffff0000, v230
	v_lshlrev_b32_e32 v160, 16, v223
	v_and_b32_e32 v161, 0xffff0000, v223
	v_lshlrev_b32_e32 v168, 16, v231
	v_and_b32_e32 v169, 0xffff0000, v231
	v_lshlrev_b32_e32 v162, 16, v224
	v_and_b32_e32 v163, 0xffff0000, v224
	v_lshlrev_b32_e32 v170, 16, v232
	v_and_b32_e32 v171, 0xffff0000, v232
	v_lshlrev_b32_e32 v164, 16, v225
	v_and_b32_e32 v165, 0xffff0000, v225
	v_lshlrev_b32_e32 v172, 16, v233
	v_and_b32_e32 v173, 0xffff0000, v233
	v_pk_fma_f32 v[20:21], v[20:21], v[166:167], v[158:159]
	v_pk_fma_f32 v[22:23], v[22:23], v[168:169], v[160:161]
	v_pk_fma_f32 v[16:17], v[16:17], v[170:171], v[162:163]
	v_pk_fma_f32 v[18:19], v[18:19], v[172:173], v[164:165]
	global_store_dwordx4 v155, v[20:23], s[76:77] offset:512 nt
	global_store_dwordx4 v155, v[16:19], s[76:77] offset:528 nt
	s_waitcnt vmcnt(12)
	v_fmamk_f32 v157, v252, 0x3a800000, v154
	v_rsq_f32_e32 v157, v157
	s_add_u32 s76, s80, 0xb0000
	s_addc_u32 s77, s81, 0
	v_mul_f32_e32 v157, 0xbfb8aa3b, v157
	v_mul_f32_e32 v8, v8, v157
	v_mul_f32_e32 v9, v9, v157
	v_mul_f32_e32 v10, v10, v157
	v_mul_f32_e32 v11, v11, v157
	v_mul_f32_e32 v12, v12, v157
	v_mul_f32_e32 v13, v13, v157
	v_mul_f32_e32 v14, v14, v157
	v_mul_f32_e32 v15, v15, v157
	v_exp_f32_e32 v8, v8
	v_exp_f32_e32 v9, v9
	v_exp_f32_e32 v10, v10
	v_exp_f32_e32 v11, v11
	v_exp_f32_e32 v12, v12
	v_exp_f32_e32 v13, v13
	v_exp_f32_e32 v14, v14
	v_exp_f32_e32 v15, v15
	v_add_f32_e32 v8, 1.0, v8
	v_add_f32_e32 v9, 1.0, v9
	v_add_f32_e32 v10, 1.0, v10
	v_add_f32_e32 v11, 1.0, v11
	v_add_f32_e32 v12, 1.0, v12
	v_add_f32_e32 v13, 1.0, v13
	v_add_f32_e32 v14, 1.0, v14
	v_add_f32_e32 v15, 1.0, v15
	v_rcp_f32_e32 v8, v8
	v_rcp_f32_e32 v9, v9
	v_rcp_f32_e32 v10, v10
	v_rcp_f32_e32 v11, v11
	v_rcp_f32_e32 v12, v12
	v_rcp_f32_e32 v13, v13
	v_rcp_f32_e32 v14, v14
	v_rcp_f32_e32 v15, v15
	v_lshlrev_b32_e32 v158, 16, v236
	v_and_b32_e32 v159, 0xffff0000, v236
	v_lshlrev_b32_e32 v166, 16, v244
	v_and_b32_e32 v167, 0xffff0000, v244
	v_lshlrev_b32_e32 v160, 16, v237
	v_and_b32_e32 v161, 0xffff0000, v237
	v_lshlrev_b32_e32 v168, 16, v245
	v_and_b32_e32 v169, 0xffff0000, v245
	v_lshlrev_b32_e32 v162, 16, v238
	v_and_b32_e32 v163, 0xffff0000, v238
	v_lshlrev_b32_e32 v170, 16, v246
	v_and_b32_e32 v171, 0xffff0000, v246
	v_lshlrev_b32_e32 v164, 16, v239
	v_and_b32_e32 v165, 0xffff0000, v239
	v_lshlrev_b32_e32 v172, 16, v247
	v_and_b32_e32 v173, 0xffff0000, v247
	v_pk_fma_f32 v[12:13], v[12:13], v[166:167], v[158:159]
	v_pk_fma_f32 v[14:15], v[14:15], v[168:169], v[160:161]
	v_pk_fma_f32 v[8:9], v[8:9], v[170:171], v[162:163]
	v_pk_fma_f32 v[10:11], v[10:11], v[172:173], v[164:165]
	global_store_dwordx4 v155, v[12:15], s[76:77] nt
	global_store_dwordx4 v155, v[8:11], s[76:77] offset:16 nt
	v_mul_f32_e32 v0, v0, v157
	v_mul_f32_e32 v1, v1, v157
	v_mul_f32_e32 v2, v2, v157
	v_mul_f32_e32 v3, v3, v157
	v_mul_f32_e32 v4, v4, v157
	v_mul_f32_e32 v5, v5, v157
	v_mul_f32_e32 v6, v6, v157
	v_mul_f32_e32 v7, v7, v157
	v_exp_f32_e32 v0, v0
	v_exp_f32_e32 v1, v1
	v_exp_f32_e32 v2, v2
	v_exp_f32_e32 v3, v3
	v_exp_f32_e32 v4, v4
	v_exp_f32_e32 v5, v5
	v_exp_f32_e32 v6, v6
	v_exp_f32_e32 v7, v7
	v_add_f32_e32 v0, 1.0, v0
	v_add_f32_e32 v1, 1.0, v1
	v_add_f32_e32 v2, 1.0, v2
	v_add_f32_e32 v3, 1.0, v3
	v_add_f32_e32 v4, 1.0, v4
	v_add_f32_e32 v5, 1.0, v5
	v_add_f32_e32 v6, 1.0, v6
	v_add_f32_e32 v7, 1.0, v7
	v_rcp_f32_e32 v0, v0
	v_rcp_f32_e32 v1, v1
	v_rcp_f32_e32 v2, v2
	v_rcp_f32_e32 v3, v3
	v_rcp_f32_e32 v4, v4
	v_rcp_f32_e32 v5, v5
	v_rcp_f32_e32 v6, v6
	v_rcp_f32_e32 v7, v7
	v_lshlrev_b32_e32 v158, 16, v240
	v_and_b32_e32 v159, 0xffff0000, v240
	v_lshlrev_b32_e32 v166, 16, v248
	v_and_b32_e32 v167, 0xffff0000, v248
	v_lshlrev_b32_e32 v160, 16, v241
	v_and_b32_e32 v161, 0xffff0000, v241
	v_lshlrev_b32_e32 v168, 16, v249
	v_and_b32_e32 v169, 0xffff0000, v249
	v_lshlrev_b32_e32 v162, 16, v242
	v_and_b32_e32 v163, 0xffff0000, v242
	v_lshlrev_b32_e32 v170, 16, v250
	v_and_b32_e32 v171, 0xffff0000, v250
	v_lshlrev_b32_e32 v164, 16, v243
	v_and_b32_e32 v165, 0xffff0000, v243
	v_lshlrev_b32_e32 v172, 16, v251
	v_and_b32_e32 v173, 0xffff0000, v251
	v_pk_fma_f32 v[4:5], v[4:5], v[166:167], v[158:159]
	v_pk_fma_f32 v[6:7], v[6:7], v[168:169], v[160:161]
	v_pk_fma_f32 v[0:1], v[0:1], v[170:171], v[162:163]
	v_pk_fma_f32 v[2:3], v[2:3], v[172:173], v[164:165]
	global_store_dwordx4 v155, v[4:7], s[76:77] offset:512 nt
	global_store_dwordx4 v155, v[0:3], s[76:77] offset:528 nt
	s_cbranch_vccnz .LBB0_716
	s_andn2_b64 vcc, exec, s[4:5]
	s_cbranch_vccnz .LBB0_715
	s_barrier
	s_branch .LBB0_715
